# phase-1 leftover tiles (64 of 1344) moved into phase 2 on workgroups 0-63; gla_prep units handed out by atomic ticket after rw_prep; RWKV waves s_setprio 3
# speedup vs baseline: 1.2070x; 1.0078x over previous
; #define LAS __attribute__((address_space(3)))
; DEVINL unsigned xb_add(unsigned* p_, unsigned v) { return __hip_atomic_fetch_add(p_, v, __ATOMIC_RELAXED, __HIP_MEMORY_SCOPE_AGENT); }
; DEVINL unsigned xb_xcc_id() { return (unsigned)__builtin_amdgcn_s_getreg((3 << 11) | 20) & 0xFu; }
; DEVINL XcdBarrier xcd_barrier_post(unsigned* bar, volatile LAS unsigned* st) {
;   XcdBarrier b; b.bar = bar; b.x = xb_xcc_id(); b.st = st;
;   if (threadIdx.x == 0) (void)xb_add(&bar[XB_XCNT(b.x)], 1u);
;   return b;
; __global__ void __launch_bounds__(512, 2) k_mega(Params p) {
;   cg::grid_group grid = cg::this_grid();
;   __shared__ uint4 xb_words;
;   unsigned* bar = (unsigned*)(p.ws + O_BAR);
;   if (threadIdx.x == 0) xb_words = make_uint4(0u, 0u, 0u, 0u);
;   __syncthreads();
;   XcdBarrier xb = xcd_barrier_post(bar, (volatile LAS unsigned*)&xb_words);
_Z6k_mega6Params:
	s_load_dwordx4 s[92:95], s[0:1], 0x100
	s_mov_b32 s98, 0
	s_add_u32 s6, s0, 0x108
	s_addc_u32 s7, s1, 0
	v_and_b32_e32 v189, 0x3ff, v0
	v_cmp_eq_u32_e64 s[8:9], 0, v189
	s_mov_b64 s[4:5], exec
	s_nop 0
	v_writelane_b32 v254, s8, 0
	s_nop 1
	v_writelane_b32 v254, s9, 1
	s_and_b64 s[8:9], s[4:5], s[8:9]
	s_mov_b64 exec, s[8:9]
	v_mov_b32_e32 v2, 0
	v_mov_b32_e32 v3, v2
	v_mov_b32_e32 v4, v2
	v_mov_b32_e32 v5, v2
	ds_write_b128 v2, v[2:5]
	s_or_b64 exec, exec, s[4:5]
	s_load_dword s54, s[0:1], 0x110
	s_load_dwordx16 s[8:23], s[0:1], 0xc0
	s_waitcnt lgkmcnt(0)
	s_add_u32 s96, s92, 0x217c0000
	s_barrier
	v_writelane_b32 v254, s8, 2
	s_getreg_b32 s3, hwreg(HW_REG_XCC_ID, 0, 4)
	s_addc_u32 s97, s93, 0
	v_writelane_b32 v254, s9, 3
	v_writelane_b32 v254, s10, 4
	v_writelane_b32 v254, s11, 5
	v_writelane_b32 v254, s12, 6
	v_writelane_b32 v254, s13, 7
	v_writelane_b32 v254, s14, 8
	v_writelane_b32 v254, s15, 9
	v_writelane_b32 v254, s16, 10
	v_writelane_b32 v254, s17, 11
	v_writelane_b32 v254, s18, 12
	v_writelane_b32 v254, s19, 13
	v_writelane_b32 v254, s20, 14
	v_writelane_b32 v254, s21, 15
	v_writelane_b32 v254, s22, 16
	s_and_b32 s33, s3, 15
	v_writelane_b32 v254, s23, 17
	s_mov_b64 s[4:5], exec
	v_readlane_b32 s8, v254, 0
	v_readlane_b32 s9, v254, 1
	s_and_b64 s[8:9], s[4:5], s[8:9]
	s_mov_b64 exec, s[8:9]
	s_cbranch_execz .LBB0_5
	s_mov_b64 s[8:9], exec
	v_mbcnt_lo_u32_b32 v1, s8, 0
	v_mbcnt_hi_u32_b32 v1, s9, v1
	v_cmp_eq_u32_e32 vcc, 0, v1
	s_and_b64 s[10:11], exec, vcc
	s_mov_b64 exec, s[10:11]
	s_cbranch_execz .LBB0_5
	s_lshl_b32 s3, s33, 8
	s_bcnt1_i32_b64 s8, s[8:9]
	v_mov_b32_e32 v1, s3
	v_mov_b32_e32 v2, s8
	global_atomic_add v1, v2, s[96:97] offset:1024

; DEVINL float sigm(float x) { return 1.f / (1.f + __expf(-x)); }
; template <int EPI, bool GATHER>
; DEVINL void gemm_tile(const Params& p, const u16* __restrict__ A, int lda, const int* __restrict__ rowidx,
;                       const u16* __restrict__ Bt, int ldb, int K, int brow, int bcol, int orow, int ocol) {
;     ...
; #pragma unroll
;   for (int ai = 0; ai < 2; ++ai)
; #pragma unroll
;     for (int m = 0; m < 4; ++m) {
;       const int rA = row0 + ai * HALF + m * 16 + (odd ? 2 : 0);
;       float gate[2] = {0.f, 0.f};
;       if (EPI == EPI_MOE2) { gate[0] = ((const float*)(ws + O_SELG))[rA]; gate[1] = ((const float*)(ws + O_SELG))[rA + 1]; }
; #pragma unroll
;       for (int bj = 0; bj < (EPI == EPI_HID ? 1 : 2); ++bj)
; #pragma unroll
;         for (int n = 0; n < 2; ++n) {
;           const int cc = bj * HALF + n * 16;
;           f32x4 v = acc[ai][bj][m][n];
;           if (EPI == EPI_HID) {
; #pragma unroll
;             for (int j = 0; j < 4; ++j) { const float a1 = acc[ai][0][m][n][j], a3 = acc[ai][1][m][n][j]; v[j] = a1 * sigm(a1) * a3; }
;           }
;           float lo[2], hi[2];
;           xchg_pairs(v, odd, lo, hi);
; #pragma unroll
;           for (int k = 0; k < 2; ++k) {
;             const unsigned row = (unsigned)(rA + k);
;             if (EPI == EPI_HID) {
;               *(unsigned*)(ws + O_HID + (row * 1024u + (unsigned)(colp + cc)) * 2u) = pk2(lo[k], hi[k]);
;             } else if (EPI == EPI_COLS) {
;               *(unsigned*)(ws + O_COLS + (row * (unsigned)NCP + (unsigned)(colp + cc)) * 2u) = pk2(lo[k], hi[k]);
; DEVINL void phase1(const Params& p) {
;     ...
;   for (int t = blockIdx.x; t < ntiles; t += gridDim.x) {
;     int pm = t & 31, pn = t >> 5;
;     gemm_tile<EPI_COLS, false>(p, A, 2048, nullptr, Bt, 2048, 2048, pm * 256, pn * 256, pm * 256, pn * 256);
.Lq_p1entry:
	s_andn2_b64 vcc, exec, s[58:59]
	s_waitcnt lgkmcnt(0)
	s_barrier
	s_cbranch_vccnz .LBB0_231
	s_add_u32 s0, s92, 0x4c00000
	s_mov_b64 s[56:57], s[96:97]
	s_addc_u32 s1, s93, 0
	s_lshl_b32 s3, s2, 8
	s_lshl_b32 s40, s94, 8
	s_lshl_b32 s41, s2, 3
	s_lshl_b32 s42, s94, 3
	s_mov_b32 s5, 0
	s_add_i32 s43, 16, 0x10000
	s_add_i32 s44, 16, 0x14000
	s_add_i32 s45, 16, 0x18000
	s_mov_b64 s[8:9], 0x80
	s_add_i32 s46, 16, 0x1c000
	s_mov_b64 s[18:19], 0x80080
	s_mov_b64 s[22:23], 0x2000100
	s_mov_b64 s[24:25], 0x100
	s_mov_b64 s[36:37], 0x2080100
	s_mov_b64 s[38:39], 0x80100
	s_mov_b64 s[68:69], 0x2000180
	s_mov_b64 s[70:71], 0x180
	s_mov_b64 s[72:73], 0x2080180
	v_mov_b32_e32 v140, 1
	s_mov_b32 s47, s2
	s_branch .LBB0_224
.LBB0_223:
	s_or_b64 exec, exec, s[6:7]
	v_and_b32_e32 v130, 1, v141
	v_add_u32_e32 v128, s48, v145
	v_lshlrev_b32_e32 v129, 2, v144
	v_lshlrev_b32_e32 v131, 1, v130
	v_or3_b32 v128, v128, v131, v129
	v_or_b32_e32 v129, s78, v143
	v_cmp_eq_u32_e32 vcc, 0, v130
	v_sub_u32_e32 v129, v129, v130
	s_movk_i32 s4, 0x2a00
	v_cndmask_b32_e32 v130, v124, v126, vcc
	v_cndmask_b32_e32 v131, v125, v127, vcc
	v_lshl_add_u32 v129, v142, 5, v129
	v_mov_b32_dpp v130, v130 quad_perm:[1,0,3,2] row_mask:0xf bank_mask:0xf bound_ctrl:1
	v_cndmask_b32_e32 v124, v130, v124, vcc
	v_cndmask_b32_e32 v126, v126, v130, vcc
	v_mov_b32_dpp v131, v131 quad_perm:[1,0,3,2] row_mask:0xf bank_mask:0xf bound_ctrl:1
	v_cvt_pk_bf16_f32 v124, v124, v126
	v_mul_lo_u32 v126, v128, s4
	v_cndmask_b32_e32 v125, v131, v125, vcc
	v_cndmask_b32_e32 v127, v127, v131, vcc
	v_add_lshl_u32 v128, v126, v129, 1
	global_store_dword v128, v124, s[0:1]
	v_cvt_pk_bf16_f32 v124, v125, v127
	v_add_u32_e32 v125, 0x2a00, v126
	v_add_lshl_u32 v127, v125, v129, 1
	global_store_dword v127, v124, s[0:1]
	v_cndmask_b32_e32 v124, v116, v118, vcc
	v_cndmask_b32_e32 v127, v117, v119, vcc
	s_nop 0
	v_mov_b32_dpp v124, v124 quad_perm:[1,0,3,2] row_mask:0xf bank_mask:0xf bound_ctrl:1
	v_mov_b32_dpp v127, v127 quad_perm:[1,0,3,2] row_mask:0xf bank_mask:0xf bound_ctrl:1
	v_cndmask_b32_e32 v116, v124, v116, vcc
	v_cndmask_b32_e32 v118, v118, v124, vcc
	v_add_u32_e32 v124, 16, v129
	v_cndmask_b32_e32 v117, v127, v117, vcc
	v_cndmask_b32_e32 v119, v119, v127, vcc
	v_cvt_pk_bf16_f32 v116, v116, v118
	v_add_lshl_u32 v118, v126, v124, 1
	global_store_dword v118, v116, s[0:1]
	v_cvt_pk_bf16_f32 v116, v117, v119
	v_add_lshl_u32 v117, v125, v124, 1
	global_store_dword v117, v116, s[0:1]
	v_cndmask_b32_e32 v117, v120, v122, vcc
	v_cndmask_b32_e32 v118, v121, v123, vcc
	v_add_u32_e32 v116, 0x80, v129
	v_mov_b32_dpp v117, v117 quad_perm:[1,0,3,2] row_mask:0xf bank_mask:0xf bound_ctrl:1
	v_mov_b32_dpp v118, v118 quad_perm:[1,0,3,2] row_mask:0xf bank_mask:0xf bound_ctrl:1
	v_cndmask_b32_e32 v119, v117, v120, vcc
	v_cndmask_b32_e32 v117, v122, v117, vcc
	v_cndmask_b32_e32 v120, v118, v121, vcc
	v_cndmask_b32_e32 v118, v123, v118, vcc
	v_cvt_pk_bf16_f32 v117, v119, v117
	v_add_lshl_u32 v119, v126, v116, 1
	global_store_dword v119, v117, s[0:1]
	v_cvt_pk_bf16_f32 v117, v120, v118
	v_add_lshl_u32 v118, v125, v116, 1
	global_store_dword v118, v117, s[0:1]
	v_cndmask_b32_e32 v117, v112, v114, vcc
	v_cndmask_b32_e32 v118, v113, v115, vcc
	s_nop 0
	v_mov_b32_dpp v117, v117 quad_perm:[1,0,3,2] row_mask:0xf bank_mask:0xf bound_ctrl:1
	v_mov_b32_dpp v118, v118 quad_perm:[1,0,3,2] row_mask:0xf bank_mask:0xf bound_ctrl:1
	v_cndmask_b32_e32 v112, v117, v112, vcc
	v_cndmask_b32_e32 v114, v114, v117, vcc
	v_add_u32_e32 v117, 0x90, v129
	v_cndmask_b32_e32 v113, v118, v113, vcc
	v_cndmask_b32_e32 v115, v115, v118, vcc
	v_cvt_pk_bf16_f32 v112, v112, v114
	v_add_lshl_u32 v114, v126, v117, 1
	global_store_dword v114, v112, s[0:1]
	v_cvt_pk_bf16_f32 v112, v113, v115
	v_add_lshl_u32 v113, v125, v117, 1
	global_store_dword v113, v112, s[0:1]
	v_cndmask_b32_e32 v112, v108, v110, vcc
	v_cndmask_b32_e32 v113, v109, v111, vcc
	s_nop 0
	v_mov_b32_dpp v112, v112 quad_perm:[1,0,3,2] row_mask:0xf bank_mask:0xf bound_ctrl:1
	v_cndmask_b32_e32 v108, v112, v108, vcc
	v_cndmask_b32_e32 v110, v110, v112, vcc
	v_mov_b32_dpp v113, v113 quad_perm:[1,0,3,2] row_mask:0xf bank_mask:0xf bound_ctrl:1
	v_cvt_pk_bf16_f32 v108, v108, v110
	v_add_u32_e32 v110, 0x2a000, v126
	v_cndmask_b32_e32 v109, v113, v109, vcc
	v_cndmask_b32_e32 v111, v111, v113, vcc
	v_add_lshl_u32 v112, v110, v129, 1
	global_store_dword v112, v108, s[0:1]
	v_cvt_pk_bf16_f32 v108, v109, v111
	v_add_u32_e32 v109, 0x2ca00, v126
	v_add_lshl_u32 v111, v109, v129, 1
	global_store_dword v111, v108, s[0:1]
	v_cndmask_b32_e32 v108, v100, v102, vcc
	v_cndmask_b32_e32 v111, v101, v103, vcc
	s_nop 0
	v_mov_b32_dpp v108, v108 quad_perm:[1,0,3,2] row_mask:0xf bank_mask:0xf bound_ctrl:1
	v_mov_b32_dpp v111, v111 quad_perm:[1,0,3,2] row_mask:0xf bank_mask:0xf bound_ctrl:1
	v_cndmask_b32_e32 v100, v108, v100, vcc
	v_cndmask_b32_e32 v102, v102, v108, vcc
	v_cndmask_b32_e32 v101, v111, v101, vcc
	v_cndmask_b32_e32 v103, v103, v111, vcc
	v_cvt_pk_bf16_f32 v100, v100, v102
	v_add_lshl_u32 v102, v110, v124, 1
	global_store_dword v102, v100, s[0:1]
	v_cvt_pk_bf16_f32 v100, v101, v103
	v_add_lshl_u32 v101, v109, v124, 1
	global_store_dword v101, v100, s[0:1]
	v_cndmask_b32_e32 v100, v104, v106, vcc
	v_cndmask_b32_e32 v101, v105, v107, vcc
	s_nop 0
	v_mov_b32_dpp v100, v100 quad_perm:[1,0,3,2] row_mask:0xf bank_mask:0xf bound_ctrl:1
	v_mov_b32_dpp v101, v101 quad_perm:[1,0,3,2] row_mask:0xf bank_mask:0xf bound_ctrl:1
	v_cndmask_b32_e32 v102, v100, v104, vcc
	v_cndmask_b32_e32 v100, v106, v100, vcc
	v_cndmask_b32_e32 v103, v101, v105, vcc
	v_cndmask_b32_e32 v101, v107, v101, vcc
	v_cvt_pk_bf16_f32 v100, v102, v100
; DEVINL float sigm(float x) { return 1.f / (1.f + __expf(-x)); }
; template <int EPI, bool GATHER>
; DEVINL void gemm_tile(const Params& p, const u16* __restrict__ A, int lda, const int* __restrict__ rowidx,
;                       const u16* __restrict__ Bt, int ldb, int K, int brow, int bcol, int orow, int ocol) {
;     ...
; #pragma unroll
;   for (int ai = 0; ai < 2; ++ai)
; #pragma unroll
;     for (int m = 0; m < 4; ++m) {
;       const int rA = row0 + ai * HALF + m * 16 + (odd ? 2 : 0);
;       float gate[2] = {0.f, 0.f};
;       if (EPI == EPI_MOE2) { gate[0] = ((const float*)(ws + O_SELG))[rA]; gate[1] = ((const float*)(ws + O_SELG))[rA + 1]; }
; #pragma unroll
;       for (int bj = 0; bj < (EPI == EPI_HID ? 1 : 2); ++bj)
; #pragma unroll
;         for (int n = 0; n < 2; ++n) {
;           const int cc = bj * HALF + n * 16;
;           f32x4 v = acc[ai][bj][m][n];
;           if (EPI == EPI_HID) {
; #pragma unroll
;             for (int j = 0; j < 4; ++j) { const float a1 = acc[ai][0][m][n][j], a3 = acc[ai][1][m][n][j]; v[j] = a1 * sigm(a1) * a3; }
;           }
;           float lo[2], hi[2];
;           xchg_pairs(v, odd, lo, hi);
; #pragma unroll
;           for (int k = 0; k < 2; ++k) {
;             const unsigned row = (unsigned)(rA + k);
;             if (EPI == EPI_HID) {
;               *(unsigned*)(ws + O_HID + (row * 1024u + (unsigned)(colp + cc)) * 2u) = pk2(lo[k], hi[k]);
;             } else if (EPI == EPI_COLS) {
;               *(unsigned*)(ws + O_COLS + (row * (unsigned)NCP + (unsigned)(colp + cc)) * 2u) = pk2(lo[k], hi[k]);
	v_add_lshl_u32 v102, v110, v116, 1
	global_store_dword v102, v100, s[0:1]
	v_cvt_pk_bf16_f32 v100, v103, v101
	v_add_lshl_u32 v101, v109, v116, 1
	global_store_dword v101, v100, s[0:1]
	v_cndmask_b32_e32 v100, v96, v98, vcc
	v_cndmask_b32_e32 v101, v97, v99, vcc
	s_nop 0
	v_mov_b32_dpp v100, v100 quad_perm:[1,0,3,2] row_mask:0xf bank_mask:0xf bound_ctrl:1
	v_mov_b32_dpp v101, v101 quad_perm:[1,0,3,2] row_mask:0xf bank_mask:0xf bound_ctrl:1
	v_cndmask_b32_e32 v96, v100, v96, vcc
	v_cndmask_b32_e32 v98, v98, v100, vcc
	v_cndmask_b32_e32 v97, v101, v97, vcc
	v_cndmask_b32_e32 v99, v99, v101, vcc
	v_cvt_pk_bf16_f32 v96, v96, v98
	v_add_lshl_u32 v98, v110, v117, 1
	global_store_dword v98, v96, s[0:1]
	v_cvt_pk_bf16_f32 v96, v97, v99
	v_add_lshl_u32 v97, v109, v117, 1
	global_store_dword v97, v96, s[0:1]
	v_cndmask_b32_e32 v96, v92, v94, vcc
	v_cndmask_b32_e32 v97, v93, v95, vcc
	s_nop 0
	v_mov_b32_dpp v96, v96 quad_perm:[1,0,3,2] row_mask:0xf bank_mask:0xf bound_ctrl:1
	v_cndmask_b32_e32 v92, v96, v92, vcc
	v_cndmask_b32_e32 v94, v94, v96, vcc
	v_mov_b32_dpp v97, v97 quad_perm:[1,0,3,2] row_mask:0xf bank_mask:0xf bound_ctrl:1
	v_cvt_pk_bf16_f32 v92, v92, v94
	v_add_u32_e32 v94, 0x54000, v126
	v_cndmask_b32_e32 v93, v97, v93, vcc
	v_cndmask_b32_e32 v95, v95, v97, vcc
	v_add_lshl_u32 v96, v94, v129, 1
	global_store_dword v96, v92, s[0:1]
	v_cvt_pk_bf16_f32 v92, v93, v95
	v_add_u32_e32 v93, 0x56a00, v126
	v_add_lshl_u32 v95, v93, v129, 1
	global_store_dword v95, v92, s[0:1]
	v_cndmask_b32_e32 v92, v84, v86, vcc
	v_cndmask_b32_e32 v95, v85, v87, vcc
	s_nop 0
	v_mov_b32_dpp v92, v92 quad_perm:[1,0,3,2] row_mask:0xf bank_mask:0xf bound_ctrl:1
	v_mov_b32_dpp v95, v95 quad_perm:[1,0,3,2] row_mask:0xf bank_mask:0xf bound_ctrl:1
	v_cndmask_b32_e32 v84, v92, v84, vcc
	v_cndmask_b32_e32 v86, v86, v92, vcc
	v_cndmask_b32_e32 v85, v95, v85, vcc
	v_cndmask_b32_e32 v87, v87, v95, vcc
	v_cvt_pk_bf16_f32 v84, v84, v86
	v_add_lshl_u32 v86, v94, v124, 1
	global_store_dword v86, v84, s[0:1]
	v_cvt_pk_bf16_f32 v84, v85, v87
	v_add_lshl_u32 v85, v93, v124, 1
	global_store_dword v85, v84, s[0:1]
	v_cndmask_b32_e32 v84, v88, v90, vcc
	v_cndmask_b32_e32 v85, v89, v91, vcc
	s_nop 0
	v_mov_b32_dpp v84, v84 quad_perm:[1,0,3,2] row_mask:0xf bank_mask:0xf bound_ctrl:1
	v_mov_b32_dpp v85, v85 quad_perm:[1,0,3,2] row_mask:0xf bank_mask:0xf bound_ctrl:1
	v_cndmask_b32_e32 v86, v84, v88, vcc
	v_cndmask_b32_e32 v84, v90, v84, vcc
	v_cndmask_b32_e32 v87, v85, v89, vcc
	v_cndmask_b32_e32 v85, v91, v85, vcc
	v_cvt_pk_bf16_f32 v84, v86, v84
	v_add_lshl_u32 v86, v94, v116, 1
	global_store_dword v86, v84, s[0:1]
	v_cvt_pk_bf16_f32 v84, v87, v85
	v_add_lshl_u32 v85, v93, v116, 1
	global_store_dword v85, v84, s[0:1]
	v_cndmask_b32_e32 v84, v80, v82, vcc
	v_cndmask_b32_e32 v85, v81, v83, vcc
	s_nop 0
	v_mov_b32_dpp v84, v84 quad_perm:[1,0,3,2] row_mask:0xf bank_mask:0xf bound_ctrl:1
	v_mov_b32_dpp v85, v85 quad_perm:[1,0,3,2] row_mask:0xf bank_mask:0xf bound_ctrl:1
	v_cndmask_b32_e32 v80, v84, v80, vcc
	v_cndmask_b32_e32 v82, v82, v84, vcc
	v_cndmask_b32_e32 v81, v85, v81, vcc
	v_cndmask_b32_e32 v83, v83, v85, vcc
	v_cvt_pk_bf16_f32 v80, v80, v82
	v_add_lshl_u32 v82, v94, v117, 1
	global_store_dword v82, v80, s[0:1]
	v_cvt_pk_bf16_f32 v80, v81, v83
	v_add_lshl_u32 v81, v93, v117, 1
	global_store_dword v81, v80, s[0:1]
	v_cndmask_b32_e32 v80, v76, v78, vcc
	v_cndmask_b32_e32 v81, v77, v79, vcc
	s_nop 0
	v_mov_b32_dpp v80, v80 quad_perm:[1,0,3,2] row_mask:0xf bank_mask:0xf bound_ctrl:1
	v_cndmask_b32_e32 v76, v80, v76, vcc
	v_cndmask_b32_e32 v78, v78, v80, vcc
	v_mov_b32_dpp v81, v81 quad_perm:[1,0,3,2] row_mask:0xf bank_mask:0xf bound_ctrl:1
	v_cvt_pk_bf16_f32 v76, v76, v78
	v_add_u32_e32 v78, 0x7e000, v126
	v_cndmask_b32_e32 v77, v81, v77, vcc
	v_cndmask_b32_e32 v79, v79, v81, vcc
	v_add_lshl_u32 v80, v78, v129, 1
	global_store_dword v80, v76, s[0:1]
	v_cvt_pk_bf16_f32 v76, v77, v79
	v_add_u32_e32 v77, 0x80a00, v126
	v_add_lshl_u32 v79, v77, v129, 1
	global_store_dword v79, v76, s[0:1]
	v_cndmask_b32_e32 v76, v68, v70, vcc
	v_cndmask_b32_e32 v79, v69, v71, vcc
	s_nop 0
	v_mov_b32_dpp v76, v76 quad_perm:[1,0,3,2] row_mask:0xf bank_mask:0xf bound_ctrl:1
	v_mov_b32_dpp v79, v79 quad_perm:[1,0,3,2] row_mask:0xf bank_mask:0xf bound_ctrl:1
	v_cndmask_b32_e32 v68, v76, v68, vcc
	v_cndmask_b32_e32 v70, v70, v76, vcc
	v_cndmask_b32_e32 v69, v79, v69, vcc
	v_cndmask_b32_e32 v71, v71, v79, vcc
	v_cvt_pk_bf16_f32 v68, v68, v70
	v_add_lshl_u32 v70, v78, v124, 1
	global_store_dword v70, v68, s[0:1]
	v_cvt_pk_bf16_f32 v68, v69, v71
	v_add_lshl_u32 v69, v77, v124, 1
	global_store_dword v69, v68, s[0:1]
	v_cndmask_b32_e32 v68, v72, v74, vcc
	v_cndmask_b32_e32 v69, v73, v75, vcc
	s_nop 0
	v_mov_b32_dpp v68, v68 quad_perm:[1,0,3,2] row_mask:0xf bank_mask:0xf bound_ctrl:1
	v_mov_b32_dpp v69, v69 quad_perm:[1,0,3,2] row_mask:0xf bank_mask:0xf bound_ctrl:1
	v_cndmask_b32_e32 v70, v68, v72, vcc
	v_cndmask_b32_e32 v68, v74, v68, vcc
	v_cndmask_b32_e32 v71, v69, v73, vcc
	v_cndmask_b32_e32 v69, v75, v69, vcc
	v_cvt_pk_bf16_f32 v68, v70, v68
	v_add_lshl_u32 v70, v78, v116, 1
	global_store_dword v70, v68, s[0:1]
	v_cvt_pk_bf16_f32 v68, v71, v69
	v_add_lshl_u32 v69, v77, v116, 1
	global_store_dword v69, v68, s[0:1]
	v_cndmask_b32_e32 v68, v60, v62, vcc
	v_cndmask_b32_e32 v69, v61, v63, vcc
	s_nop 0
	v_mov_b32_dpp v68, v68 quad_perm:[1,0,3,2] row_mask:0xf bank_mask:0xf bound_ctrl:1
	v_mov_b32_dpp v69, v69 quad_perm:[1,0,3,2] row_mask:0xf bank_mask:0xf bound_ctrl:1
	v_cndmask_b32_e32 v60, v68, v60, vcc
	v_cndmask_b32_e32 v62, v62, v68, vcc
	v_cndmask_b32_e32 v61, v69, v61, vcc
	v_cndmask_b32_e32 v63, v63, v69, vcc
; DEVINL float sigm(float x) { return 1.f / (1.f + __expf(-x)); }
; template <int EPI, bool GATHER>
; DEVINL void gemm_tile(const Params& p, const u16* __restrict__ A, int lda, const int* __restrict__ rowidx,
;                       const u16* __restrict__ Bt, int ldb, int K, int brow, int bcol, int orow, int ocol) {
;     ...
; #pragma unroll
;   for (int ai = 0; ai < 2; ++ai)
; #pragma unroll
;     for (int m = 0; m < 4; ++m) {
;       const int rA = row0 + ai * HALF + m * 16 + (odd ? 2 : 0);
;       float gate[2] = {0.f, 0.f};
;       if (EPI == EPI_MOE2) { gate[0] = ((const float*)(ws + O_SELG))[rA]; gate[1] = ((const float*)(ws + O_SELG))[rA + 1]; }
; #pragma unroll
;       for (int bj = 0; bj < (EPI == EPI_HID ? 1 : 2); ++bj)
; #pragma unroll
;         for (int n = 0; n < 2; ++n) {
;           const int cc = bj * HALF + n * 16;
;           f32x4 v = acc[ai][bj][m][n];
;           if (EPI == EPI_HID) {
; #pragma unroll
;             for (int j = 0; j < 4; ++j) { const float a1 = acc[ai][0][m][n][j], a3 = acc[ai][1][m][n][j]; v[j] = a1 * sigm(a1) * a3; }
;           }
;           float lo[2], hi[2];
;           xchg_pairs(v, odd, lo, hi);
; #pragma unroll
;           for (int k = 0; k < 2; ++k) {
;             const unsigned row = (unsigned)(rA + k);
;             if (EPI == EPI_HID) {
;               *(unsigned*)(ws + O_HID + (row * 1024u + (unsigned)(colp + cc)) * 2u) = pk2(lo[k], hi[k]);
;             } else if (EPI == EPI_COLS) {
;               *(unsigned*)(ws + O_COLS + (row * (unsigned)NCP + (unsigned)(colp + cc)) * 2u) = pk2(lo[k], hi[k]);
	v_cvt_pk_bf16_f32 v60, v60, v62
	v_add_lshl_u32 v62, v78, v117, 1
	global_store_dword v62, v60, s[0:1]
	v_cvt_pk_bf16_f32 v60, v61, v63
	v_add_lshl_u32 v61, v77, v117, 1
	global_store_dword v61, v60, s[0:1]
	v_cndmask_b32_e32 v60, v64, v66, vcc
	v_cndmask_b32_e32 v61, v65, v67, vcc
	s_nop 0
	v_mov_b32_dpp v60, v60 quad_perm:[1,0,3,2] row_mask:0xf bank_mask:0xf bound_ctrl:1
	v_cndmask_b32_e32 v62, v60, v64, vcc
	v_cndmask_b32_e32 v60, v66, v60, vcc
	v_mov_b32_dpp v61, v61 quad_perm:[1,0,3,2] row_mask:0xf bank_mask:0xf bound_ctrl:1
	v_cvt_pk_bf16_f32 v60, v62, v60
	v_add_u32_e32 v62, 0x150000, v126
	v_cndmask_b32_e32 v63, v61, v65, vcc
	v_cndmask_b32_e32 v61, v67, v61, vcc
	v_add_lshl_u32 v64, v62, v129, 1
	global_store_dword v64, v60, s[0:1]
	v_cvt_pk_bf16_f32 v60, v63, v61
	v_add_u32_e32 v61, 0x152a00, v126
	v_add_lshl_u32 v63, v61, v129, 1
	global_store_dword v63, v60, s[0:1]
	v_cndmask_b32_e32 v60, v52, v54, vcc
	v_cndmask_b32_e32 v63, v53, v55, vcc
	s_nop 0
	v_mov_b32_dpp v60, v60 quad_perm:[1,0,3,2] row_mask:0xf bank_mask:0xf bound_ctrl:1
	v_mov_b32_dpp v63, v63 quad_perm:[1,0,3,2] row_mask:0xf bank_mask:0xf bound_ctrl:1
	v_cndmask_b32_e32 v52, v60, v52, vcc
	v_cndmask_b32_e32 v54, v54, v60, vcc
	v_cndmask_b32_e32 v53, v63, v53, vcc
	v_cndmask_b32_e32 v55, v55, v63, vcc
	v_cvt_pk_bf16_f32 v52, v52, v54
	v_add_lshl_u32 v54, v62, v124, 1
	global_store_dword v54, v52, s[0:1]
	v_cvt_pk_bf16_f32 v52, v53, v55
	v_add_lshl_u32 v53, v61, v124, 1
	global_store_dword v53, v52, s[0:1]
	v_cndmask_b32_e32 v52, v56, v58, vcc
	v_cndmask_b32_e32 v53, v57, v59, vcc
	s_nop 0
	v_mov_b32_dpp v52, v52 quad_perm:[1,0,3,2] row_mask:0xf bank_mask:0xf bound_ctrl:1
	v_mov_b32_dpp v53, v53 quad_perm:[1,0,3,2] row_mask:0xf bank_mask:0xf bound_ctrl:1
	v_cndmask_b32_e32 v54, v52, v56, vcc
	v_cndmask_b32_e32 v52, v58, v52, vcc
	v_cndmask_b32_e32 v55, v53, v57, vcc
	v_cndmask_b32_e32 v53, v59, v53, vcc
	v_cvt_pk_bf16_f32 v52, v54, v52
	v_add_lshl_u32 v54, v62, v116, 1
	global_store_dword v54, v52, s[0:1]
	v_cvt_pk_bf16_f32 v52, v55, v53
	v_add_lshl_u32 v53, v61, v116, 1
	global_store_dword v53, v52, s[0:1]
	v_cndmask_b32_e32 v52, v48, v50, vcc
	v_cndmask_b32_e32 v53, v49, v51, vcc
	s_nop 0
	v_mov_b32_dpp v52, v52 quad_perm:[1,0,3,2] row_mask:0xf bank_mask:0xf bound_ctrl:1
	v_mov_b32_dpp v53, v53 quad_perm:[1,0,3,2] row_mask:0xf bank_mask:0xf bound_ctrl:1
	v_cndmask_b32_e32 v48, v52, v48, vcc
	v_cndmask_b32_e32 v50, v50, v52, vcc
	v_cndmask_b32_e32 v49, v53, v49, vcc
	v_cndmask_b32_e32 v51, v51, v53, vcc
	v_cvt_pk_bf16_f32 v48, v48, v50
	v_add_lshl_u32 v50, v62, v117, 1
	global_store_dword v50, v48, s[0:1]
	v_cvt_pk_bf16_f32 v48, v49, v51
	v_add_lshl_u32 v49, v61, v117, 1
	global_store_dword v49, v48, s[0:1]
	v_cndmask_b32_e32 v48, v44, v46, vcc
	v_cndmask_b32_e32 v49, v45, v47, vcc
	s_nop 0
	v_mov_b32_dpp v48, v48 quad_perm:[1,0,3,2] row_mask:0xf bank_mask:0xf bound_ctrl:1
	v_cndmask_b32_e32 v44, v48, v44, vcc
	v_cndmask_b32_e32 v46, v46, v48, vcc
	v_mov_b32_dpp v49, v49 quad_perm:[1,0,3,2] row_mask:0xf bank_mask:0xf bound_ctrl:1
	v_cvt_pk_bf16_f32 v44, v44, v46
	v_add_u32_e32 v46, 0x17a000, v126
	v_cndmask_b32_e32 v45, v49, v45, vcc
	v_cndmask_b32_e32 v47, v47, v49, vcc
	v_add_lshl_u32 v48, v46, v129, 1
	global_store_dword v48, v44, s[0:1]
	v_cvt_pk_bf16_f32 v44, v45, v47
	v_add_u32_e32 v45, 0x17ca00, v126
	v_add_lshl_u32 v47, v45, v129, 1
	global_store_dword v47, v44, s[0:1]
	v_cndmask_b32_e32 v44, v36, v38, vcc
	v_cndmask_b32_e32 v47, v37, v39, vcc
	s_nop 0
	v_mov_b32_dpp v44, v44 quad_perm:[1,0,3,2] row_mask:0xf bank_mask:0xf bound_ctrl:1
	v_mov_b32_dpp v47, v47 quad_perm:[1,0,3,2] row_mask:0xf bank_mask:0xf bound_ctrl:1
	v_cndmask_b32_e32 v36, v44, v36, vcc
	v_cndmask_b32_e32 v38, v38, v44, vcc
	v_cndmask_b32_e32 v37, v47, v37, vcc
	v_cndmask_b32_e32 v39, v39, v47, vcc
	v_cvt_pk_bf16_f32 v36, v36, v38
	v_add_lshl_u32 v38, v46, v124, 1
	global_store_dword v38, v36, s[0:1]
	v_cvt_pk_bf16_f32 v36, v37, v39
	v_add_lshl_u32 v37, v45, v124, 1
	global_store_dword v37, v36, s[0:1]
	v_cndmask_b32_e32 v36, v40, v42, vcc
	v_cndmask_b32_e32 v37, v41, v43, vcc
	s_nop 0
	v_mov_b32_dpp v36, v36 quad_perm:[1,0,3,2] row_mask:0xf bank_mask:0xf bound_ctrl:1
	v_mov_b32_dpp v37, v37 quad_perm:[1,0,3,2] row_mask:0xf bank_mask:0xf bound_ctrl:1
	v_cndmask_b32_e32 v38, v36, v40, vcc
	v_cndmask_b32_e32 v36, v42, v36, vcc
	v_cndmask_b32_e32 v39, v37, v41, vcc
	v_cndmask_b32_e32 v37, v43, v37, vcc
	v_cvt_pk_bf16_f32 v36, v38, v36
	v_add_lshl_u32 v38, v46, v116, 1
	global_store_dword v38, v36, s[0:1]
	v_cvt_pk_bf16_f32 v36, v39, v37
	v_add_lshl_u32 v37, v45, v116, 1
	global_store_dword v37, v36, s[0:1]
	v_cndmask_b32_e32 v36, v32, v34, vcc
	v_cndmask_b32_e32 v37, v33, v35, vcc
	s_nop 0
	v_mov_b32_dpp v36, v36 quad_perm:[1,0,3,2] row_mask:0xf bank_mask:0xf bound_ctrl:1
	v_mov_b32_dpp v37, v37 quad_perm:[1,0,3,2] row_mask:0xf bank_mask:0xf bound_ctrl:1
	v_cndmask_b32_e32 v32, v36, v32, vcc
	v_cndmask_b32_e32 v34, v34, v36, vcc
	v_cndmask_b32_e32 v33, v37, v33, vcc
	v_cndmask_b32_e32 v35, v35, v37, vcc
	v_cvt_pk_bf16_f32 v32, v32, v34
	v_add_lshl_u32 v34, v46, v117, 1
	global_store_dword v34, v32, s[0:1]
	v_cvt_pk_bf16_f32 v32, v33, v35
; DEVINL float sigm(float x) { return 1.f / (1.f + __expf(-x)); }
; template <int EPI, bool GATHER>
; DEVINL void gemm_tile(const Params& p, const u16* __restrict__ A, int lda, const int* __restrict__ rowidx,
;                       const u16* __restrict__ Bt, int ldb, int K, int brow, int bcol, int orow, int ocol) {
;     ...
; #pragma unroll
;   for (int ai = 0; ai < 2; ++ai)
; #pragma unroll
;     for (int m = 0; m < 4; ++m) {
;       const int rA = row0 + ai * HALF + m * 16 + (odd ? 2 : 0);
;       float gate[2] = {0.f, 0.f};
;       if (EPI == EPI_MOE2) { gate[0] = ((const float*)(ws + O_SELG))[rA]; gate[1] = ((const float*)(ws + O_SELG))[rA + 1]; }
; #pragma unroll
;       for (int bj = 0; bj < (EPI == EPI_HID ? 1 : 2); ++bj)
; #pragma unroll
;         for (int n = 0; n < 2; ++n) {
;           const int cc = bj * HALF + n * 16;
;           f32x4 v = acc[ai][bj][m][n];
;           if (EPI == EPI_HID) {
; #pragma unroll
;             for (int j = 0; j < 4; ++j) { const float a1 = acc[ai][0][m][n][j], a3 = acc[ai][1][m][n][j]; v[j] = a1 * sigm(a1) * a3; }
;           }
;           float lo[2], hi[2];
;           xchg_pairs(v, odd, lo, hi);
; #pragma unroll
;           for (int k = 0; k < 2; ++k) {
;             const unsigned row = (unsigned)(rA + k);
;             if (EPI == EPI_HID) {
;               *(unsigned*)(ws + O_HID + (row * 1024u + (unsigned)(colp + cc)) * 2u) = pk2(lo[k], hi[k]);
;             } else if (EPI == EPI_COLS) {
;               *(unsigned*)(ws + O_COLS + (row * (unsigned)NCP + (unsigned)(colp + cc)) * 2u) = pk2(lo[k], hi[k]);
; DEVINL void phase1(const Params& p) {
;     ...
;   for (int t = blockIdx.x; t < ntiles; t += gridDim.x) {
;     int pm = t & 31, pn = t >> 5;
;     gemm_tile<EPI_COLS, false>(p, A, 2048, nullptr, Bt, 2048, 2048, pm * 256, pn * 256, pm * 256, pn * 256);
	v_add_lshl_u32 v33, v45, v117, 1
	global_store_dword v33, v32, s[0:1]
	v_cndmask_b32_e32 v32, v28, v30, vcc
	v_cndmask_b32_e32 v33, v29, v31, vcc
	s_nop 0
	v_mov_b32_dpp v32, v32 quad_perm:[1,0,3,2] row_mask:0xf bank_mask:0xf bound_ctrl:1
	v_cndmask_b32_e32 v28, v32, v28, vcc
	v_cndmask_b32_e32 v30, v30, v32, vcc
	v_mov_b32_dpp v33, v33 quad_perm:[1,0,3,2] row_mask:0xf bank_mask:0xf bound_ctrl:1
	v_cvt_pk_bf16_f32 v28, v28, v30
	v_add_u32_e32 v30, 0x1a4000, v126
	v_cndmask_b32_e32 v29, v33, v29, vcc
	v_cndmask_b32_e32 v31, v31, v33, vcc
	v_add_lshl_u32 v32, v30, v129, 1
	global_store_dword v32, v28, s[0:1]
	v_cvt_pk_bf16_f32 v28, v29, v31
	v_add_u32_e32 v29, 0x1a6a00, v126
	v_add_lshl_u32 v31, v29, v129, 1
	global_store_dword v31, v28, s[0:1]
	v_cndmask_b32_e32 v28, v20, v22, vcc
	v_cndmask_b32_e32 v31, v21, v23, vcc
	s_nop 0
	v_mov_b32_dpp v28, v28 quad_perm:[1,0,3,2] row_mask:0xf bank_mask:0xf bound_ctrl:1
	v_mov_b32_dpp v31, v31 quad_perm:[1,0,3,2] row_mask:0xf bank_mask:0xf bound_ctrl:1
	v_cndmask_b32_e32 v20, v28, v20, vcc
	v_cndmask_b32_e32 v22, v22, v28, vcc
	v_cndmask_b32_e32 v21, v31, v21, vcc
	v_cndmask_b32_e32 v23, v23, v31, vcc
	v_cvt_pk_bf16_f32 v20, v20, v22
	v_add_lshl_u32 v22, v30, v124, 1
	global_store_dword v22, v20, s[0:1]
	v_cvt_pk_bf16_f32 v20, v21, v23
	v_add_lshl_u32 v21, v29, v124, 1
	global_store_dword v21, v20, s[0:1]
	v_cndmask_b32_e32 v20, v24, v26, vcc
	v_cndmask_b32_e32 v21, v25, v27, vcc
	s_nop 0
	v_mov_b32_dpp v20, v20 quad_perm:[1,0,3,2] row_mask:0xf bank_mask:0xf bound_ctrl:1
	v_mov_b32_dpp v21, v21 quad_perm:[1,0,3,2] row_mask:0xf bank_mask:0xf bound_ctrl:1
	v_cndmask_b32_e32 v22, v20, v24, vcc
	v_cndmask_b32_e32 v20, v26, v20, vcc
	v_cndmask_b32_e32 v23, v21, v25, vcc
	v_cndmask_b32_e32 v21, v27, v21, vcc
	v_cvt_pk_bf16_f32 v20, v22, v20
	v_add_lshl_u32 v22, v30, v116, 1
	global_store_dword v22, v20, s[0:1]
	v_cvt_pk_bf16_f32 v20, v23, v21
	v_add_lshl_u32 v21, v29, v116, 1
	global_store_dword v21, v20, s[0:1]
	v_cndmask_b32_e32 v20, v16, v18, vcc
	v_cndmask_b32_e32 v21, v17, v19, vcc
	s_nop 0
	v_mov_b32_dpp v20, v20 quad_perm:[1,0,3,2] row_mask:0xf bank_mask:0xf bound_ctrl:1
	v_mov_b32_dpp v21, v21 quad_perm:[1,0,3,2] row_mask:0xf bank_mask:0xf bound_ctrl:1
	v_cndmask_b32_e32 v16, v20, v16, vcc
	v_cndmask_b32_e32 v18, v18, v20, vcc
	v_cndmask_b32_e32 v17, v21, v17, vcc
	v_cndmask_b32_e32 v19, v19, v21, vcc
	v_cvt_pk_bf16_f32 v16, v16, v18
	v_add_lshl_u32 v18, v30, v117, 1
	global_store_dword v18, v16, s[0:1]
	v_cvt_pk_bf16_f32 v16, v17, v19
	v_add_lshl_u32 v17, v29, v117, 1
	global_store_dword v17, v16, s[0:1]
	v_cndmask_b32_e32 v16, v12, v14, vcc
	v_cndmask_b32_e32 v17, v13, v15, vcc
	s_nop 0
	v_mov_b32_dpp v16, v16 quad_perm:[1,0,3,2] row_mask:0xf bank_mask:0xf bound_ctrl:1
	v_cndmask_b32_e32 v12, v16, v12, vcc
	v_cndmask_b32_e32 v14, v14, v16, vcc
	v_mov_b32_dpp v17, v17 quad_perm:[1,0,3,2] row_mask:0xf bank_mask:0xf bound_ctrl:1
	v_cvt_pk_bf16_f32 v12, v12, v14
	v_add_u32_e32 v14, 0x1ce000, v126
	v_cndmask_b32_e32 v13, v17, v13, vcc
	v_cndmask_b32_e32 v15, v15, v17, vcc
	v_add_lshl_u32 v16, v14, v129, 1
	global_store_dword v16, v12, s[0:1]
	v_cvt_pk_bf16_f32 v12, v13, v15
	v_add_u32_e32 v13, 0x1d0a00, v126
	v_add_lshl_u32 v15, v13, v129, 1
	global_store_dword v15, v12, s[0:1]
	v_cndmask_b32_e32 v12, v4, v6, vcc
	v_cndmask_b32_e32 v15, v5, v7, vcc
	s_nop 0
	v_mov_b32_dpp v12, v12 quad_perm:[1,0,3,2] row_mask:0xf bank_mask:0xf bound_ctrl:1
	v_mov_b32_dpp v15, v15 quad_perm:[1,0,3,2] row_mask:0xf bank_mask:0xf bound_ctrl:1
	v_cndmask_b32_e32 v4, v12, v4, vcc
	v_cndmask_b32_e32 v6, v6, v12, vcc
	v_cndmask_b32_e32 v5, v15, v5, vcc
	v_cndmask_b32_e32 v7, v7, v15, vcc
	v_cvt_pk_bf16_f32 v4, v4, v6
	v_add_lshl_u32 v6, v14, v124, 1
	global_store_dword v6, v4, s[0:1]
	v_cvt_pk_bf16_f32 v4, v5, v7
	v_add_lshl_u32 v5, v13, v124, 1
	global_store_dword v5, v4, s[0:1]
	v_cndmask_b32_e32 v4, v8, v10, vcc
	v_cndmask_b32_e32 v5, v9, v11, vcc
	s_nop 0
	v_mov_b32_dpp v4, v4 quad_perm:[1,0,3,2] row_mask:0xf bank_mask:0xf bound_ctrl:1
	v_mov_b32_dpp v5, v5 quad_perm:[1,0,3,2] row_mask:0xf bank_mask:0xf bound_ctrl:1
	v_cndmask_b32_e32 v6, v4, v8, vcc
	v_cndmask_b32_e32 v4, v10, v4, vcc
	v_cndmask_b32_e32 v7, v5, v9, vcc
	v_cndmask_b32_e32 v5, v11, v5, vcc
	v_cvt_pk_bf16_f32 v4, v6, v4
	v_add_lshl_u32 v6, v14, v116, 1
	global_store_dword v6, v4, s[0:1]
	v_cvt_pk_bf16_f32 v4, v7, v5
	v_add_lshl_u32 v5, v13, v116, 1
	global_store_dword v5, v4, s[0:1]
	v_cndmask_b32_e32 v4, v0, v2, vcc
	v_cndmask_b32_e32 v5, v1, v3, vcc
	s_nop 0
	v_mov_b32_dpp v4, v4 quad_perm:[1,0,3,2] row_mask:0xf bank_mask:0xf bound_ctrl:1
	v_mov_b32_dpp v5, v5 quad_perm:[1,0,3,2] row_mask:0xf bank_mask:0xf bound_ctrl:1
	v_cndmask_b32_e32 v0, v4, v0, vcc
	v_cndmask_b32_e32 v2, v2, v4, vcc
	v_cndmask_b32_e32 v1, v5, v1, vcc
	v_cndmask_b32_e32 v3, v3, v5, vcc
	v_cvt_pk_bf16_f32 v0, v0, v2
	v_add_lshl_u32 v2, v14, v117, 1
	global_store_dword v2, v0, s[0:1]
	v_cvt_pk_bf16_f32 v0, v1, v3
	v_add_lshl_u32 v1, v13, v117, 1
	global_store_dword v1, v0, s[0:1]
	s_add_i32 s47, s47, s94
	s_add_i32 s3, s3, s40
	s_add_i32 s41, s41, s42
	s_cmpk_lt_i32 s47, 0x500
	s_waitcnt vmcnt(0)
	s_barrier
	s_cbranch_scc0 .LBB0_230

; DEVINL unsigned xb_ld(unsigned* p_) { return __hip_atomic_load(p_, __ATOMIC_RELAXED, __HIP_MEMORY_SCOPE_AGENT); }
; DEVINL void xcd_barrier_complete(unsigned* bar, unsigned x, unsigned& nloc, unsigned& nx) {
;   const unsigned G = gridDim.x * gridDim.y * gridDim.z;
;   unsigned sum, cnt, mine, sp = 0u;
;   for (;;) {
;     sum = 0u; cnt = 0u; mine = 0u;
; #pragma unroll
;     for (unsigned j = 0; j < 16; ++j) { const unsigned c = xb_ld(&bar[XB_XCNT(j)]); sum += c; cnt += (c > 0u) ? 1u : 0u; mine = (j == x) ? c : mine; }
; DEVINL void xcd_barrier(const XcdBarrier& b) {
;   asm volatile("s_waitcnt vmcnt(0)" ::: "memory");
;   __syncthreads();
;   if (threadIdx.x == 0) {
;     unsigned* bar = b.bar;
;     __builtin_amdgcn_s_waitcnt(0);
;     unsigned nloc = b.st[0], nx = b.st[1];
;     if (nloc == 0u) { xcd_barrier_complete(bar, b.x, nloc, nx); b.st[0] = nloc; b.st[1] = nx; }
.LBB0_231:
	s_cmp_eq_u32 s98, 1
	s_cbranch_scc1 .Lq_ret
	s_waitcnt vmcnt(0)
	s_barrier
	s_mov_b64 s[0:1], exec
	v_readlane_b32 s4, v254, 0
	v_readlane_b32 s5, v254, 1
	s_and_b64 s[4:5], s[0:1], s[4:5]
	s_mov_b64 exec, s[4:5]
	s_cbranch_execz .LBB0_283
	v_mov_b32_e32 v0, 0
	s_waitcnt vmcnt(0) expcnt(0) lgkmcnt(0)
	ds_read_b32 v2, v0
	ds_read_b32 v1, v0 offset:4
	s_waitcnt lgkmcnt(1)
	v_cmp_ne_u32_e32 vcc, 0, v2
	s_cbranch_vccnz .LBB0_247
	s_add_u32 s4, s92, 0x217c0200
	s_addc_u32 s5, s93, 0
	s_add_u32 s8, s92, 0x217c0400
	s_addc_u32 s9, s93, 0
	s_add_u32 s18, s92, 0x217c0500
	s_addc_u32 s19, s93, 0
	s_add_u32 s22, s92, 0x217c0600
	s_addc_u32 s23, s93, 0
	s_add_u32 s24, s92, 0x217c0700
	s_addc_u32 s25, s93, 0
	s_add_u32 s36, s92, 0x217c0800
	s_addc_u32 s37, s93, 0
	s_add_u32 s38, s92, 0x217c0900
	s_addc_u32 s39, s93, 0
	s_add_u32 s68, s92, 0x217c0a00
	s_addc_u32 s69, s93, 0
	s_add_u32 s70, s92, 0x217c0b00
	s_addc_u32 s71, s93, 0
	s_add_u32 s72, s92, 0x217c0c00
	s_addc_u32 s73, s93, 0
	s_add_u32 s78, s92, 0x217c0d00
	s_addc_u32 s79, s93, 0
	s_add_u32 s6, s92, 0x217c0e00
	s_addc_u32 s7, s93, 0
	s_add_u32 s40, s92, 0x217c0f00
	s_addc_u32 s41, s93, 0
	s_add_u32 s42, s92, 0x217c1000
	s_addc_u32 s43, s93, 0
	s_mov_b64 s[56:57], s[96:97]
	s_add_u32 s96, s92, 0x217c1100
	s_addc_u32 s97, s93, 0
	s_add_u32 s44, s92, 0x217c1200
	s_addc_u32 s45, s93, 0
	s_mul_i32 s3, s95, s54
	s_add_u32 s46, s92, 0x217c1300
	s_mul_i32 s3, s3, s94
	s_addc_u32 s47, s93, 0
	s_mov_b32 s55, 1
	s_branch .LBB0_235

; DEVINL int otid() { int t = threadIdx.x; asm volatile("" : "+v"(t)); return t; }
; DEVINL void phase1(const Params& p) {
;     ...
;   for (int t = blockIdx.x; t < ntiles; t += gridDim.x) {
;     int pm = t & 31, pn = t >> 5;
;     gemm_tile<EPI_COLS, false>(p, A, 2048, nullptr, Bt, 2048, 2048, pm * 256, pn * 256, pm * 256, pn * 256);
; DEVINL void phase2(const Params& p) {
;   const int bid = blockIdx.x, nb = gridDim.x, tid = otid();
;   for (int u = bid; u < 512; u += nb) gla_prep_unit(p, u);
;   for (int u = bid; u < 256; u += nb) rw_prep_unit(p, u);
; }
.LBB0_283:
	s_or_b64 exec, exec, s[0:1]
	s_cmpk_lt_i32 s2, 0x200
	v_mov_b32_e32 v0, v189
	s_cselect_b64 s[68:69], -1, 0
	s_cmpk_gt_i32 s2, 0x1ff
	s_waitcnt lgkmcnt(0)
	s_barrier
	s_cbranch_scc1 .LBB0_334
	v_writelane_b32 v255, s80, 20
	v_writelane_b32 v255, s81, 21
	v_writelane_b32 v255, s82, 22
	v_writelane_b32 v255, s83, 23
	v_writelane_b32 v255, s84, 24
	v_writelane_b32 v255, s85, 25
	v_writelane_b32 v255, s86, 26
	v_writelane_b32 v255, s87, 27
	s_cmp_ge_u32 s2, 64
	s_cbranch_scc1 .Lq_skip
	v_writelane_b32 v255, s18, 0
	v_writelane_b32 v255, s19, 1
	v_writelane_b32 v255, s23, 2
	v_writelane_b32 v255, s25, 3
	v_writelane_b32 v255, s68, 4
	v_writelane_b32 v255, s69, 5
	v_writelane_b32 v255, s96, 6
	v_writelane_b32 v255, s97, 7
	s_add_u32 s2, s2, 0x500
	s_mov_b64 s[58:59], -1
	s_mov_b32 s98, 1
	s_branch .Lq_p1entry
.Lq_ret:
	v_readlane_b32 s18, v255, 0
	v_readlane_b32 s19, v255, 1
	v_readlane_b32 s23, v255, 2
	v_readlane_b32 s25, v255, 3
	v_readlane_b32 s68, v255, 4
	v_readlane_b32 s69, v255, 5
	v_readlane_b32 s96, v255, 6
	v_readlane_b32 s97, v255, 7
	s_nop 4
	s_sub_u32 s2, s2, 0x500
	s_mov_b32 s98, 0

; DEVINL float bf2f(u16 h) { return __uint_as_float(((unsigned)h) << 16); }
; DEVINL int otid() { int t = threadIdx.x; asm volatile("" : "+v"(t)); return t; }
; DEVINL void gla_prep_unit(const Params& p, int unit) {
;   const int h = unit & 3, c = (unit >> 2) & 63, b = unit >> 8;
;   char* ws = p.ws;
;   const u16* cols = (const u16*)(ws + O_COLS);
;   const int tid = otid();
;   float* afab = (float*)dynsmem;
;   float* G = (float*)(dynsmem + 8192);
;   u16* KD = (u16*)(dynsmem + 8192 + 65536);
;   u16* VL = (u16*)dynsmem;
;   const long tok0 = (long)b * S_ + c * 64;
;   for (int i = tid; i < 64 * 32; i += 512) {
;     int r = i >> 5, cc = i & 31;
;     afab[i] = bf2f(cols[(tok0 + r) * NCP + C_AF + cc]);
;   }
;   __syncthreads();
;   if (tid < 256) {
;     const int dir = tid >> 7, kk = tid & 127;
;     const float* up = dir ? p.gla_a_up_b : p.gla_a_up_f;
;     const float bias = (dir ? p.gla_a_bias_b : p.gla_a_bias_f)[h * 128 + kk];
;     float u[16];
; #pragma unroll
;     for (int r = 0; r < 16; ++r) u[r] = up[r * 512 + h * 128 + kk];
.LBB0_387:
	v_readlane_b32 s80, v255, 20
	v_readlane_b32 s81, v255, 21
	v_readlane_b32 s82, v255, 22
	v_readlane_b32 s83, v255, 23
	v_readlane_b32 s84, v255, 24
	v_readlane_b32 s85, v255, 25
	v_readlane_b32 s86, v255, 26
	v_readlane_b32 s87, v255, 27
	s_nop 4
	v_mov_b32_e32 v0, v189
	v_and_b32_e32 v1, 0x7f, v0
	v_lshlrev_b32_e32 v2, 4, v0
	v_lshrrev_b32_e32 v3, 6, v0
	s_nop 0
	v_readfirstlane_b32 s70, v3
	s_nop 3
	s_lshr_b32 s71, s70, 2
	s_bfe_u32 s6, s70, 0x10001
	v_lshrrev_b32_e32 v4, 3, v0
	v_mul_u32_u24_e32 v4, 0x5400, v4
	v_and_b32_e32 v5, 7, v0
	v_lshl_add_u32 v4, v5, 3, v4
	v_add_u32_e32 v4, 0x1800, v4
	v_lshrrev_b32_e32 v5, 4, v0
	v_mul_u32_u24_e32 v5, 0x5400, v5
	v_and_b32_e32 v6, 15, v0
	v_lshl_add_u32 v5, v6, 4, v5
	v_lshrrev_b32_e32 v6, 5, v0
	v_mul_u32_u24_e32 v6, 0x5400, v6
	v_and_b32_e32 v7, 31, v0
	v_lshl_add_u32 v6, v7, 4, v6
	v_lshlrev_b32_e32 v7, 2, v1
	v_and_b32_e32 v8, 0xff, v0
	v_lshrrev_b32_e32 v9, 8, v0
	v_lshlrev_b32_e32 v10, 1, v8
	v_lshl_add_u32 v10, v9, 14, v10
	v_add_u32_e32 v10, 0xa010, v10
	v_lshlrev_b32_e32 v11, 7, v8
	v_lshl_add_u32 v11, v9, 6, v11
	s_lshl_b32 s7, s71, 6
	s_lshl_b32 s8, s6, 12
	s_add_u32 s7, s7, s8
	s_add_u32 s7, s7, 16
	v_mov_b32_e32 v12, s7
	s_lshl_b32 s7, s6, 1
	s_add_u32 s7, s7, s71
	s_lshl_b32 s7, s7, 9
	s_add_u32 s7, s7, 106512
	v_add_u32_e32 v13, s7, v7
	s_xor_b32 s8, s6, 1
	s_lshl_b32 s8, s8, 1
	s_add_u32 s8, s8, s71
	s_lshl_b32 s8, s8, 9
	s_add_u32 s8, s8, 106512
	v_add_u32_e32 v14, s8, v7
	s_lshl_b32 s8, s71, 9
	s_add_u32 s8, s8, 108560
	v_add_u32_e32 v15, s8, v7
	s_lshl_b32 s8, s6, 13
	s_add_u32 s8, s8, 24592
	v_lshl_add_u32 v16, v1, 1, s8
	s_lshl_b32 s8, s71, 15
	s_lshl_b32 s9, s6, 14
	s_add_u32 s8, s8, s9
	s_add_u32 s8, s8, 40976
	v_add_u32_e32 v17, s8, v7
	v_lshlrev_b32_e32 v18, 7, v1
	s_lshl_b32 s8, s6, 6
	v_add_u32_e32 v18, s8, v18
	v_and_b32_e32 v19, 15, v0
	v_lshrrev_b32_e32 v20, 2, v19
	v_and_b32_e32 v21, 3, v19
	v_lshlrev_b32_e32 v20, 5, v20
	v_lshl_add_u32 v20, v21, 2, v20
	v_lshrrev_b32_e32 v21, 4, v0
	v_lshlrev_b32_e32 v22, 9, v21
	v_lshl_add_u32 v22, v20, 2, v22
	v_add_u32_e32 v22, 0xa010, v22
	v_lshlrev_b32_e32 v23, 8, v21
	v_lshl_add_u32 v23, v20, 1, v23
	v_add_u32_e32 v23, 0x2010, v23
	s_cmp_eq_u32 s71, 0
	s_cselect_b32 s36, s80, s84
	s_cselect_b32 s37, s81, s85
	s_cselect_b32 s38, s82, s86
	s_cselect_b32 s39, s83, s87
	s_xor_b32 s40, s71, s6
.Lgl_unit:
	s_cmp_lg_u32 s70, 0
	s_cbranch_scc1 .Lgl_nofetch
	s_mov_b64 exec, 1
	v_mov_b32_e32 v27, 1
	v_mov_b32_e32 v28, 0
	global_atomic_add v29, v28, v27, s[96:97] offset:4 sc0
	s_waitcnt vmcnt(0)
	v_mov_b32_e32 v28, 8
	ds_write_b32 v28, v29
	s_waitcnt lgkmcnt(0)
	s_mov_b64 exec, -1
.Lgl_nofetch:
	s_barrier
	v_mov_b32_e32 v28, 8
	ds_read_b32 v29, v28
	s_waitcnt lgkmcnt(0)
	v_readfirstlane_b32 s3, v29
	s_nop 3
	s_cmp_ge_u32 s3, 0x200
	s_cbranch_scc1 .Lgl_done
	s_and_b32 s41, s3, 3
	s_bfe_u32 s42, s3, 0x60002
	s_lshr_b32 s43, s3, 8
	s_lshl_b32 s44, s43, 12
	s_lshl_b32 s45, s42, 6
	s_add_u32 s44, s44, s45
	s_mul_i32 s44, s44, 0x5400
	s_add_u32 s46, s92, s44
	s_addc_u32 s47, s93, 0
	s_add_u32 s46, s46, 0x4c00000
	s_addc_u32 s47, s47, 0
	global_load_dwordx2 v[82:83], v4, s[46:47]
	s_lshl_b32 s48, s41, 8
	s_add_u32 s48, s46, s48
	s_addc_u32 s49, s47, 0
	global_load_dwordx4 v[84:87], v5, s[48:49]
	global_load_dwordx4 v[92:95], v5, s[48:49] offset:1024
	s_add_u32 s50, s48, 0xa8000
	s_addc_u32 s51, s49, 0
	global_load_dwordx4 v[88:91], v5, s[50:51]
	global_load_dwordx4 v[96:99], v5, s[50:51] offset:1024
	s_lshl_b32 s48, s41, 9
	s_add_u32 s48, s46, s48
	s_addc_u32 s49, s47, 0
	global_load_dwordx4 v[100:103], v6, s[48:49] offset:2048
	s_add_u32 s48, s48, 0x54000
	s_addc_u32 s49, s49, 0
	global_load_dwordx4 v[104:107], v6, s[48:49] offset:2048
	s_add_u32 s48, s48, 0x54000
	s_addc_u32 s49, s49, 0
	global_load_dwordx4 v[108:111], v6, s[48:49] offset:2048
	s_add_u32 s48, s48, 0x54000
	s_addc_u32 s49, s49, 0
	global_load_dwordx4 v[112:115], v6, s[48:49] offset:2048
	s_lshl_b32 s48, s41, 9
	v_add_u32_e32 v24, s48, v7
	global_load_dword v64, v24, s[36:37] offset:0
	global_load_dword v65, v24, s[36:37] offset:2048
	v_add_u32_e32 v24, 0x1000, v24
	global_load_dword v66, v24, s[36:37] offset:0
	global_load_dword v67, v24, s[36:37] offset:2048
	v_add_u32_e32 v24, 0x1000, v24
	global_load_dword v68, v24, s[36:37] offset:0
	global_load_dword v69, v24, s[36:37] offset:2048
	v_add_u32_e32 v24, 0x1000, v24
	global_load_dword v70, v24, s[36:37] offset:0
	global_load_dword v71, v24, s[36:37] offset:2048
	v_add_u32_e32 v24, 0x1000, v24
	global_load_dword v72, v24, s[36:37] offset:0
	global_load_dword v73, v24, s[36:37] offset:2048
	v_add_u32_e32 v24, 0x1000, v24
	global_load_dword v74, v24, s[36:37] offset:0
	global_load_dword v75, v24, s[36:37] offset:2048
	v_add_u32_e32 v24, 0x1000, v24
	global_load_dword v76, v24, s[36:37] offset:0
	global_load_dword v77, v24, s[36:37] offset:2048
	v_add_u32_e32 v24, 0x1000, v24
	global_load_dword v78, v24, s[36:37] offset:0
	global_load_dword v79, v24, s[36:37] offset:2048
	v_add_u32_e32 v25, s48, v7
	global_load_dword v80, v25, s[38:39]
	s_waitcnt vmcnt(25)
	v_lshlrev_b32_e32 v116, 16, v82
	v_and_b32_e32 v117, 0xffff0000, v82
	v_lshlrev_b32_e32 v118, 16, v83
	v_and_b32_e32 v119, 0xffff0000, v83
	ds_write_b128 v2, v[116:119] offset:16
	s_waitcnt vmcnt(21)
	ds_write_b128 v2, v[84:87] offset:8208
	ds_write_b128 v2, v[92:95] offset:24592
	ds_write_b128 v2, v[88:91] offset:16400
	ds_write_b128 v2, v[96:99] offset:32784
	s_waitcnt vmcnt(17)
	v_add_u32_e32 v26, 0x8000, v2
	ds_write_b128 v2, v[100:103] offset:40976
	ds_write_b128 v2, v[104:107] offset:49168
	ds_write_b128 v26, v[108:111] offset:24592
	ds_write_b128 v26, v[112:115] offset:32784
	s_waitcnt lgkmcnt(0)
	s_barrier
; DEVINL float logsig(float z) { return fminf(z, 0.f) - __logf(1.f + __expf(-fabsf(z))); }
; DEVINL int fragpos(int idx) { const int w = idx & 31; return (idx & ~31) + (((w & 15) >> 2) << 3) + (w & 3) + ((w >> 4) << 2); }
; DEVINL void gla_prep_unit(const Params& p, int unit) {
;     ...
;     for (int r = 0; r < 16; ++r) u[r] = up[r * 512 + h * 128 + kk];
;     float* Gc = G + dir * 64 * 128 + kk;
;     for (int i = 0; i < 64; ++i) {
;       float z = bias;
; #pragma unroll
;       for (int r = 0; r < 16; ++r) z += afab[i * 32 + dir * 16 + r] * u[r];
;       Gc[i * 128] = logsig(z) * (1.f / 16.f);
;     ...
; #pragma unroll 8
;   for (int idx = tid; idx < 64 * 256; idx += 512) {
;     int i = idx >> 8, vc = idx & 255;
;     VL[vc * 72 + fragpos(i)] = cols[(tok0 + i) * NCP + C_V + h * 256 + vc];
;   }
;   __syncthreads();
;   for (int pc = tid; pc < 4096; pc += 512) {
;     int row = pc >> 3, ch = pc & 7;
;     if (row < 256) {
;       int dir = row >> 7, kk = row & 127;
;       uint4 v = *(const uint4*)(KD + row * 72 + ch * 8);
;       long hb = ((long)(dir * 2 + b) * 4 + h);
;       *(uint4*)((u16*)(ws + O_KDT) + ((hb * 64 + c) * 128 + kk) * 64 + ch * 8) = v;
;     } else {
;       int vc = row - 256;
;       uint4 v = *(const uint4*)(VL + vc * 72 + ch * 8);
;       long hb = ((long)b * 4 + h);
;       *(uint4*)((u16*)(ws + O_VT) + ((hb * 64 + c) * 256 + vc) * 64 + ch * 8) = v;
	ds_read_u16 v192, v10 offset:0
	ds_read_u16 v193, v10 offset:512
	ds_read_u16 v194, v10 offset:1024
	ds_read_u16 v195, v10 offset:1536
	ds_read_u16 v196, v10 offset:2048
	ds_read_u16 v197, v10 offset:2560
	ds_read_u16 v198, v10 offset:3072
	ds_read_u16 v199, v10 offset:3584
	ds_read_u16 v200, v10 offset:4096
	ds_read_u16 v201, v10 offset:4608
	ds_read_u16 v202, v10 offset:5120
	ds_read_u16 v203, v10 offset:5632
	ds_read_u16 v204, v10 offset:6144
	ds_read_u16 v205, v10 offset:6656
	ds_read_u16 v206, v10 offset:7168
	ds_read_u16 v207, v10 offset:7680
	ds_read_u16 v208, v10 offset:8192
	ds_read_u16 v209, v10 offset:8704
	ds_read_u16 v210, v10 offset:9216
	ds_read_u16 v211, v10 offset:9728
	ds_read_u16 v212, v10 offset:10240
	ds_read_u16 v213, v10 offset:10752
	ds_read_u16 v214, v10 offset:11264
	ds_read_u16 v215, v10 offset:11776
	ds_read_u16 v216, v10 offset:12288
	ds_read_u16 v217, v10 offset:12800
	ds_read_u16 v218, v10 offset:13312
	ds_read_u16 v219, v10 offset:13824
	ds_read_u16 v220, v10 offset:14336
	ds_read_u16 v221, v10 offset:14848
	ds_read_u16 v222, v10 offset:15360
	ds_read_u16 v223, v10 offset:15872
	s_lshl_b32 s48, s43, 2
	s_add_u32 s48, s48, s41
	s_lshl_b32 s48, s48, 6
	s_add_u32 s48, s48, s42
	s_lshl_b32 s48, s48, 15
	s_add_u32 s48, s92, s48
	s_addc_u32 s49, s93, 0
	s_add_u32 s48, s48, 0x1a400000
	s_addc_u32 s49, s49, 0
	s_waitcnt lgkmcnt(0)
	v_lshl_or_b32 v144, v193, 16, v192
	v_lshl_or_b32 v145, v195, 16, v194
	v_lshl_or_b32 v146, v209, 16, v208
	v_lshl_or_b32 v147, v211, 16, v210
	v_lshl_or_b32 v148, v197, 16, v196
	v_lshl_or_b32 v149, v199, 16, v198
	v_lshl_or_b32 v150, v213, 16, v212
	v_lshl_or_b32 v151, v215, 16, v214
	v_lshl_or_b32 v152, v201, 16, v200
	v_lshl_or_b32 v153, v203, 16, v202
	v_lshl_or_b32 v154, v217, 16, v216
	v_lshl_or_b32 v155, v219, 16, v218
	v_lshl_or_b32 v156, v205, 16, v204
	v_lshl_or_b32 v157, v207, 16, v206
	v_lshl_or_b32 v158, v221, 16, v220
	v_lshl_or_b32 v159, v223, 16, v222
	global_store_dwordx4 v11, v[144:147], s[48:49] offset:0
	global_store_dwordx4 v11, v[148:151], s[48:49] offset:16
	global_store_dwordx4 v11, v[152:155], s[48:49] offset:32
	global_store_dwordx4 v11, v[156:159], s[48:49] offset:48
	s_waitcnt vmcnt(4)
	s_mov_b32 s52, 0xbfb8aa3b
	s_mov_b32 s53, 0x3f317217
	ds_read_b128 v[116:119], v12 offset:0
	ds_read_b128 v[120:123], v12 offset:16
	ds_read_b128 v[124:127], v12 offset:32
	ds_read_b128 v[128:131], v12 offset:48
	v_mov_b32_e32 v32, v80
	s_waitcnt lgkmcnt(3)
	v_fmac_f32_e32 v32, v116, v64
	v_fmac_f32_e32 v32, v117, v65
	v_fmac_f32_e32 v32, v118, v66
	v_fmac_f32_e32 v32, v119, v67
	s_waitcnt lgkmcnt(2)
	v_fmac_f32_e32 v32, v120, v68
	v_fmac_f32_e32 v32, v121, v69
	v_fmac_f32_e32 v32, v122, v70
	v_fmac_f32_e32 v32, v123, v71
	s_waitcnt lgkmcnt(1)
	v_fmac_f32_e32 v32, v124, v72
	v_fmac_f32_e32 v32, v125, v73
	v_fmac_f32_e32 v32, v126, v74
	v_fmac_f32_e32 v32, v127, v75
	s_waitcnt lgkmcnt(0)
	v_fmac_f32_e32 v32, v128, v76
	v_fmac_f32_e32 v32, v129, v77
	v_fmac_f32_e32 v32, v130, v78
	v_fmac_f32_e32 v32, v131, v79
	v_min_f32_e32 v132, 0, v32
	v_mul_f32_e64 v32, |v32|, s52
	v_exp_f32_e32 v32, v32
	s_nop 0
	v_add_f32_e32 v32, 1.0, v32
	v_log_f32_e32 v32, v32
	s_nop 0
	v_mul_f32_e32 v133, 0x3f317217, v32
	v_fma_f32 v133, v32, s53, -v133
	v_fmac_f32_e32 v133, 0x3377d1cf, v32
	v_fmac_f32_e32 v133, 0x3f317217, v32
	v_sub_f32_e32 v32, v132, v133
	v_mul_f32_e32 v32, 0x3d800000, v32
	ds_read_b128 v[116:119], v12 offset:128
	ds_read_b128 v[120:123], v12 offset:144
	ds_read_b128 v[124:127], v12 offset:160
	ds_read_b128 v[128:131], v12 offset:176
	v_mov_b32_e32 v33, v80
	s_waitcnt lgkmcnt(3)
	v_fmac_f32_e32 v33, v116, v64
	v_fmac_f32_e32 v33, v117, v65
	v_fmac_f32_e32 v33, v118, v66
	v_fmac_f32_e32 v33, v119, v67
	s_waitcnt lgkmcnt(2)
	v_fmac_f32_e32 v33, v120, v68
	v_fmac_f32_e32 v33, v121, v69
	v_fmac_f32_e32 v33, v122, v70
	v_fmac_f32_e32 v33, v123, v71
	s_waitcnt lgkmcnt(1)
	v_fmac_f32_e32 v33, v124, v72
	v_fmac_f32_e32 v33, v125, v73
	v_fmac_f32_e32 v33, v126, v74
	v_fmac_f32_e32 v33, v127, v75
	s_waitcnt lgkmcnt(0)
	v_fmac_f32_e32 v33, v128, v76
	v_fmac_f32_e32 v33, v129, v77
	v_fmac_f32_e32 v33, v130, v78
	v_fmac_f32_e32 v33, v131, v79
	v_min_f32_e32 v132, 0, v33
	v_mul_f32_e64 v33, |v33|, s52
	v_exp_f32_e32 v33, v33
	s_nop 0
	v_add_f32_e32 v33, 1.0, v33
	v_log_f32_e32 v33, v33
	s_nop 0
	v_mul_f32_e32 v133, 0x3f317217, v33
	v_fma_f32 v133, v33, s53, -v133
	v_fmac_f32_e32 v133, 0x3377d1cf, v33
	v_fmac_f32_e32 v133, 0x3f317217, v33
	v_sub_f32_e32 v33, v132, v133
	v_mul_f32_e32 v33, 0x3d800000, v33
	ds_read_b128 v[116:119], v12 offset:256
	ds_read_b128 v[120:123], v12 offset:272
	ds_read_b128 v[124:127], v12 offset:288
	ds_read_b128 v[128:131], v12 offset:304
	v_mov_b32_e32 v34, v80
	s_waitcnt lgkmcnt(3)
	v_fmac_f32_e32 v34, v116, v64
	v_fmac_f32_e32 v34, v117, v65
	v_fmac_f32_e32 v34, v118, v66
	v_fmac_f32_e32 v34, v119, v67
	s_waitcnt lgkmcnt(2)
	v_fmac_f32_e32 v34, v120, v68
	v_fmac_f32_e32 v34, v121, v69
	v_fmac_f32_e32 v34, v122, v70
	v_fmac_f32_e32 v34, v123, v71
	s_waitcnt lgkmcnt(1)
	v_fmac_f32_e32 v34, v124, v72
	v_fmac_f32_e32 v34, v125, v73
	v_fmac_f32_e32 v34, v126, v74
	v_fmac_f32_e32 v34, v127, v75
	s_waitcnt lgkmcnt(0)
	v_fmac_f32_e32 v34, v128, v76
	v_fmac_f32_e32 v34, v129, v77
	v_fmac_f32_e32 v34, v130, v78
	v_fmac_f32_e32 v34, v131, v79
	v_min_f32_e32 v132, 0, v34
	v_mul_f32_e64 v34, |v34|, s52
	v_exp_f32_e32 v34, v34
	s_nop 0
	v_add_f32_e32 v34, 1.0, v34
	v_log_f32_e32 v34, v34
	s_nop 0
	v_mul_f32_e32 v133, 0x3f317217, v34
	v_fma_f32 v133, v34, s53, -v133
	v_fmac_f32_e32 v133, 0x3377d1cf, v34
	v_fmac_f32_e32 v133, 0x3f317217, v34
	v_sub_f32_e32 v34, v132, v133
	v_mul_f32_e32 v34, 0x3d800000, v34
	ds_read_b128 v[116:119], v12 offset:384
	ds_read_b128 v[120:123], v12 offset:400
	ds_read_b128 v[124:127], v12 offset:416
	ds_read_b128 v[128:131], v12 offset:432
	v_mov_b32_e32 v35, v80
	s_waitcnt lgkmcnt(3)
; DEVINL float logsig(float z) { return fminf(z, 0.f) - __logf(1.f + __expf(-fabsf(z))); }
; DEVINL void gla_prep_unit(const Params& p, int unit) {
;     ...
;     for (int i = 0; i < 64; ++i) {
;       float z = bias;
; #pragma unroll
;       for (int r = 0; r < 16; ++r) z += afab[i * 32 + dir * 16 + r] * u[r];
;       Gc[i * 128] = logsig(z) * (1.f / 16.f);
	v_fmac_f32_e32 v35, v116, v64
	v_fmac_f32_e32 v35, v117, v65
	v_fmac_f32_e32 v35, v118, v66
	v_fmac_f32_e32 v35, v119, v67
	s_waitcnt lgkmcnt(2)
	v_fmac_f32_e32 v35, v120, v68
	v_fmac_f32_e32 v35, v121, v69
	v_fmac_f32_e32 v35, v122, v70
	v_fmac_f32_e32 v35, v123, v71
	s_waitcnt lgkmcnt(1)
	v_fmac_f32_e32 v35, v124, v72
	v_fmac_f32_e32 v35, v125, v73
	v_fmac_f32_e32 v35, v126, v74
	v_fmac_f32_e32 v35, v127, v75
	s_waitcnt lgkmcnt(0)
	v_fmac_f32_e32 v35, v128, v76
	v_fmac_f32_e32 v35, v129, v77
	v_fmac_f32_e32 v35, v130, v78
	v_fmac_f32_e32 v35, v131, v79
	v_min_f32_e32 v132, 0, v35
	v_mul_f32_e64 v35, |v35|, s52
	v_exp_f32_e32 v35, v35
	s_nop 0
	v_add_f32_e32 v35, 1.0, v35
	v_log_f32_e32 v35, v35
	s_nop 0
	v_mul_f32_e32 v133, 0x3f317217, v35
	v_fma_f32 v133, v35, s53, -v133
	v_fmac_f32_e32 v133, 0x3377d1cf, v35
	v_fmac_f32_e32 v133, 0x3f317217, v35
	v_sub_f32_e32 v35, v132, v133
	v_mul_f32_e32 v35, 0x3d800000, v35
	ds_read_b128 v[116:119], v12 offset:512
	ds_read_b128 v[120:123], v12 offset:528
	ds_read_b128 v[124:127], v12 offset:544
	ds_read_b128 v[128:131], v12 offset:560
	v_mov_b32_e32 v36, v80
	s_waitcnt lgkmcnt(3)
	v_fmac_f32_e32 v36, v116, v64
	v_fmac_f32_e32 v36, v117, v65
	v_fmac_f32_e32 v36, v118, v66
	v_fmac_f32_e32 v36, v119, v67
	s_waitcnt lgkmcnt(2)
	v_fmac_f32_e32 v36, v120, v68
	v_fmac_f32_e32 v36, v121, v69
	v_fmac_f32_e32 v36, v122, v70
	v_fmac_f32_e32 v36, v123, v71
	s_waitcnt lgkmcnt(1)
	v_fmac_f32_e32 v36, v124, v72
	v_fmac_f32_e32 v36, v125, v73
	v_fmac_f32_e32 v36, v126, v74
	v_fmac_f32_e32 v36, v127, v75
	s_waitcnt lgkmcnt(0)
	v_fmac_f32_e32 v36, v128, v76
	v_fmac_f32_e32 v36, v129, v77
	v_fmac_f32_e32 v36, v130, v78
	v_fmac_f32_e32 v36, v131, v79
	v_min_f32_e32 v132, 0, v36
	v_mul_f32_e64 v36, |v36|, s52
	v_exp_f32_e32 v36, v36
	s_nop 0
	v_add_f32_e32 v36, 1.0, v36
	v_log_f32_e32 v36, v36
	s_nop 0
	v_mul_f32_e32 v133, 0x3f317217, v36
	v_fma_f32 v133, v36, s53, -v133
	v_fmac_f32_e32 v133, 0x3377d1cf, v36
	v_fmac_f32_e32 v133, 0x3f317217, v36
	v_sub_f32_e32 v36, v132, v133
	v_mul_f32_e32 v36, 0x3d800000, v36
	ds_read_b128 v[116:119], v12 offset:640
	ds_read_b128 v[120:123], v12 offset:656
	ds_read_b128 v[124:127], v12 offset:672
	ds_read_b128 v[128:131], v12 offset:688
	v_mov_b32_e32 v37, v80
	s_waitcnt lgkmcnt(3)
	v_fmac_f32_e32 v37, v116, v64
	v_fmac_f32_e32 v37, v117, v65
	v_fmac_f32_e32 v37, v118, v66
	v_fmac_f32_e32 v37, v119, v67
	s_waitcnt lgkmcnt(2)
	v_fmac_f32_e32 v37, v120, v68
	v_fmac_f32_e32 v37, v121, v69
	v_fmac_f32_e32 v37, v122, v70
	v_fmac_f32_e32 v37, v123, v71
	s_waitcnt lgkmcnt(1)
	v_fmac_f32_e32 v37, v124, v72
	v_fmac_f32_e32 v37, v125, v73
	v_fmac_f32_e32 v37, v126, v74
	v_fmac_f32_e32 v37, v127, v75
	s_waitcnt lgkmcnt(0)
	v_fmac_f32_e32 v37, v128, v76
	v_fmac_f32_e32 v37, v129, v77
	v_fmac_f32_e32 v37, v130, v78
	v_fmac_f32_e32 v37, v131, v79
	v_min_f32_e32 v132, 0, v37
	v_mul_f32_e64 v37, |v37|, s52
	v_exp_f32_e32 v37, v37
	s_nop 0
	v_add_f32_e32 v37, 1.0, v37
	v_log_f32_e32 v37, v37
	s_nop 0
	v_mul_f32_e32 v133, 0x3f317217, v37
	v_fma_f32 v133, v37, s53, -v133
	v_fmac_f32_e32 v133, 0x3377d1cf, v37
	v_fmac_f32_e32 v133, 0x3f317217, v37
	v_sub_f32_e32 v37, v132, v133
	v_mul_f32_e32 v37, 0x3d800000, v37
	ds_read_b128 v[116:119], v12 offset:768
	ds_read_b128 v[120:123], v12 offset:784
	ds_read_b128 v[124:127], v12 offset:800
	ds_read_b128 v[128:131], v12 offset:816
	v_mov_b32_e32 v38, v80
	s_waitcnt lgkmcnt(3)
	v_fmac_f32_e32 v38, v116, v64
	v_fmac_f32_e32 v38, v117, v65
	v_fmac_f32_e32 v38, v118, v66
	v_fmac_f32_e32 v38, v119, v67
	s_waitcnt lgkmcnt(2)
	v_fmac_f32_e32 v38, v120, v68
	v_fmac_f32_e32 v38, v121, v69
	v_fmac_f32_e32 v38, v122, v70
	v_fmac_f32_e32 v38, v123, v71
	s_waitcnt lgkmcnt(1)
	v_fmac_f32_e32 v38, v124, v72
	v_fmac_f32_e32 v38, v125, v73
	v_fmac_f32_e32 v38, v126, v74
	v_fmac_f32_e32 v38, v127, v75
	s_waitcnt lgkmcnt(0)
	v_fmac_f32_e32 v38, v128, v76
	v_fmac_f32_e32 v38, v129, v77
	v_fmac_f32_e32 v38, v130, v78
	v_fmac_f32_e32 v38, v131, v79
	v_min_f32_e32 v132, 0, v38
	v_mul_f32_e64 v38, |v38|, s52
	v_exp_f32_e32 v38, v38
	s_nop 0
	v_add_f32_e32 v38, 1.0, v38
	v_log_f32_e32 v38, v38
	s_nop 0
	v_mul_f32_e32 v133, 0x3f317217, v38
	v_fma_f32 v133, v38, s53, -v133
	v_fmac_f32_e32 v133, 0x3377d1cf, v38
	v_fmac_f32_e32 v133, 0x3f317217, v38
	v_sub_f32_e32 v38, v132, v133
	v_mul_f32_e32 v38, 0x3d800000, v38
	ds_read_b128 v[116:119], v12 offset:896
	ds_read_b128 v[120:123], v12 offset:912
	ds_read_b128 v[124:127], v12 offset:928
	ds_read_b128 v[128:131], v12 offset:944
	v_mov_b32_e32 v39, v80
	s_waitcnt lgkmcnt(3)
	v_fmac_f32_e32 v39, v116, v64
	v_fmac_f32_e32 v39, v117, v65
	v_fmac_f32_e32 v39, v118, v66
	v_fmac_f32_e32 v39, v119, v67
	s_waitcnt lgkmcnt(2)
	v_fmac_f32_e32 v39, v120, v68
	v_fmac_f32_e32 v39, v121, v69
	v_fmac_f32_e32 v39, v122, v70
	v_fmac_f32_e32 v39, v123, v71
	s_waitcnt lgkmcnt(1)
	v_fmac_f32_e32 v39, v124, v72
	v_fmac_f32_e32 v39, v125, v73
	v_fmac_f32_e32 v39, v126, v74
	v_fmac_f32_e32 v39, v127, v75
	s_waitcnt lgkmcnt(0)
	v_fmac_f32_e32 v39, v128, v76
	v_fmac_f32_e32 v39, v129, v77
	v_fmac_f32_e32 v39, v130, v78
	v_fmac_f32_e32 v39, v131, v79
	v_min_f32_e32 v132, 0, v39
	v_mul_f32_e64 v39, |v39|, s52
	v_exp_f32_e32 v39, v39
	s_nop 0
	v_add_f32_e32 v39, 1.0, v39
	v_log_f32_e32 v39, v39
	s_nop 0
	v_mul_f32_e32 v133, 0x3f317217, v39
	v_fma_f32 v133, v39, s53, -v133
	v_fmac_f32_e32 v133, 0x3377d1cf, v39
	v_fmac_f32_e32 v133, 0x3f317217, v39
	v_sub_f32_e32 v39, v132, v133
	v_mul_f32_e32 v39, 0x3d800000, v39
	ds_read_b128 v[116:119], v12 offset:1024
	ds_read_b128 v[120:123], v12 offset:1040
	ds_read_b128 v[124:127], v12 offset:1056
	ds_read_b128 v[128:131], v12 offset:1072
	v_mov_b32_e32 v40, v80
	s_waitcnt lgkmcnt(3)
; DEVINL float logsig(float z) { return fminf(z, 0.f) - __logf(1.f + __expf(-fabsf(z))); }
; DEVINL void gla_prep_unit(const Params& p, int unit) {
;     ...
;     for (int i = 0; i < 64; ++i) {
;       float z = bias;
; #pragma unroll
;       for (int r = 0; r < 16; ++r) z += afab[i * 32 + dir * 16 + r] * u[r];
;       Gc[i * 128] = logsig(z) * (1.f / 16.f);
	v_fmac_f32_e32 v40, v116, v64
	v_fmac_f32_e32 v40, v117, v65
	v_fmac_f32_e32 v40, v118, v66
	v_fmac_f32_e32 v40, v119, v67
	s_waitcnt lgkmcnt(2)
	v_fmac_f32_e32 v40, v120, v68
	v_fmac_f32_e32 v40, v121, v69
	v_fmac_f32_e32 v40, v122, v70
	v_fmac_f32_e32 v40, v123, v71
	s_waitcnt lgkmcnt(1)
	v_fmac_f32_e32 v40, v124, v72
	v_fmac_f32_e32 v40, v125, v73
	v_fmac_f32_e32 v40, v126, v74
	v_fmac_f32_e32 v40, v127, v75
	s_waitcnt lgkmcnt(0)
	v_fmac_f32_e32 v40, v128, v76
	v_fmac_f32_e32 v40, v129, v77
	v_fmac_f32_e32 v40, v130, v78
	v_fmac_f32_e32 v40, v131, v79
	v_min_f32_e32 v132, 0, v40
	v_mul_f32_e64 v40, |v40|, s52
	v_exp_f32_e32 v40, v40
	s_nop 0
	v_add_f32_e32 v40, 1.0, v40
	v_log_f32_e32 v40, v40
	s_nop 0
	v_mul_f32_e32 v133, 0x3f317217, v40
	v_fma_f32 v133, v40, s53, -v133
	v_fmac_f32_e32 v133, 0x3377d1cf, v40
	v_fmac_f32_e32 v133, 0x3f317217, v40
	v_sub_f32_e32 v40, v132, v133
	v_mul_f32_e32 v40, 0x3d800000, v40
	ds_read_b128 v[116:119], v12 offset:1152
	ds_read_b128 v[120:123], v12 offset:1168
	ds_read_b128 v[124:127], v12 offset:1184
	ds_read_b128 v[128:131], v12 offset:1200
	v_mov_b32_e32 v41, v80
	s_waitcnt lgkmcnt(3)
	v_fmac_f32_e32 v41, v116, v64
	v_fmac_f32_e32 v41, v117, v65
	v_fmac_f32_e32 v41, v118, v66
	v_fmac_f32_e32 v41, v119, v67
	s_waitcnt lgkmcnt(2)
	v_fmac_f32_e32 v41, v120, v68
	v_fmac_f32_e32 v41, v121, v69
	v_fmac_f32_e32 v41, v122, v70
	v_fmac_f32_e32 v41, v123, v71
	s_waitcnt lgkmcnt(1)
	v_fmac_f32_e32 v41, v124, v72
	v_fmac_f32_e32 v41, v125, v73
	v_fmac_f32_e32 v41, v126, v74
	v_fmac_f32_e32 v41, v127, v75
	s_waitcnt lgkmcnt(0)
	v_fmac_f32_e32 v41, v128, v76
	v_fmac_f32_e32 v41, v129, v77
	v_fmac_f32_e32 v41, v130, v78
	v_fmac_f32_e32 v41, v131, v79
	v_min_f32_e32 v132, 0, v41
	v_mul_f32_e64 v41, |v41|, s52
	v_exp_f32_e32 v41, v41
	s_nop 0
	v_add_f32_e32 v41, 1.0, v41
	v_log_f32_e32 v41, v41
	s_nop 0
	v_mul_f32_e32 v133, 0x3f317217, v41
	v_fma_f32 v133, v41, s53, -v133
	v_fmac_f32_e32 v133, 0x3377d1cf, v41
	v_fmac_f32_e32 v133, 0x3f317217, v41
	v_sub_f32_e32 v41, v132, v133
	v_mul_f32_e32 v41, 0x3d800000, v41
	ds_read_b128 v[116:119], v12 offset:1280
	ds_read_b128 v[120:123], v12 offset:1296
	ds_read_b128 v[124:127], v12 offset:1312
	ds_read_b128 v[128:131], v12 offset:1328
	v_mov_b32_e32 v42, v80
	s_waitcnt lgkmcnt(3)
	v_fmac_f32_e32 v42, v116, v64
	v_fmac_f32_e32 v42, v117, v65
	v_fmac_f32_e32 v42, v118, v66
	v_fmac_f32_e32 v42, v119, v67
	s_waitcnt lgkmcnt(2)
	v_fmac_f32_e32 v42, v120, v68
	v_fmac_f32_e32 v42, v121, v69
	v_fmac_f32_e32 v42, v122, v70
	v_fmac_f32_e32 v42, v123, v71
	s_waitcnt lgkmcnt(1)
	v_fmac_f32_e32 v42, v124, v72
	v_fmac_f32_e32 v42, v125, v73
	v_fmac_f32_e32 v42, v126, v74
	v_fmac_f32_e32 v42, v127, v75
	s_waitcnt lgkmcnt(0)
	v_fmac_f32_e32 v42, v128, v76
	v_fmac_f32_e32 v42, v129, v77
	v_fmac_f32_e32 v42, v130, v78
	v_fmac_f32_e32 v42, v131, v79
	v_min_f32_e32 v132, 0, v42
	v_mul_f32_e64 v42, |v42|, s52
	v_exp_f32_e32 v42, v42
	s_nop 0
	v_add_f32_e32 v42, 1.0, v42
	v_log_f32_e32 v42, v42
	s_nop 0
	v_mul_f32_e32 v133, 0x3f317217, v42
	v_fma_f32 v133, v42, s53, -v133
	v_fmac_f32_e32 v133, 0x3377d1cf, v42
	v_fmac_f32_e32 v133, 0x3f317217, v42
	v_sub_f32_e32 v42, v132, v133
	v_mul_f32_e32 v42, 0x3d800000, v42
	ds_read_b128 v[116:119], v12 offset:1408
	ds_read_b128 v[120:123], v12 offset:1424
	ds_read_b128 v[124:127], v12 offset:1440
	ds_read_b128 v[128:131], v12 offset:1456
	v_mov_b32_e32 v43, v80
	s_waitcnt lgkmcnt(3)
	v_fmac_f32_e32 v43, v116, v64
	v_fmac_f32_e32 v43, v117, v65
	v_fmac_f32_e32 v43, v118, v66
	v_fmac_f32_e32 v43, v119, v67
	s_waitcnt lgkmcnt(2)
	v_fmac_f32_e32 v43, v120, v68
	v_fmac_f32_e32 v43, v121, v69
	v_fmac_f32_e32 v43, v122, v70
	v_fmac_f32_e32 v43, v123, v71
	s_waitcnt lgkmcnt(1)
	v_fmac_f32_e32 v43, v124, v72
	v_fmac_f32_e32 v43, v125, v73
	v_fmac_f32_e32 v43, v126, v74
	v_fmac_f32_e32 v43, v127, v75
	s_waitcnt lgkmcnt(0)
	v_fmac_f32_e32 v43, v128, v76
	v_fmac_f32_e32 v43, v129, v77
	v_fmac_f32_e32 v43, v130, v78
	v_fmac_f32_e32 v43, v131, v79
	v_min_f32_e32 v132, 0, v43
	v_mul_f32_e64 v43, |v43|, s52
	v_exp_f32_e32 v43, v43
	s_nop 0
	v_add_f32_e32 v43, 1.0, v43
	v_log_f32_e32 v43, v43
	s_nop 0
	v_mul_f32_e32 v133, 0x3f317217, v43
	v_fma_f32 v133, v43, s53, -v133
	v_fmac_f32_e32 v133, 0x3377d1cf, v43
	v_fmac_f32_e32 v133, 0x3f317217, v43
	v_sub_f32_e32 v43, v132, v133
	v_mul_f32_e32 v43, 0x3d800000, v43
	ds_read_b128 v[116:119], v12 offset:1536
	ds_read_b128 v[120:123], v12 offset:1552
	ds_read_b128 v[124:127], v12 offset:1568
	ds_read_b128 v[128:131], v12 offset:1584
	v_mov_b32_e32 v44, v80
	s_waitcnt lgkmcnt(3)
	v_fmac_f32_e32 v44, v116, v64
	v_fmac_f32_e32 v44, v117, v65
	v_fmac_f32_e32 v44, v118, v66
	v_fmac_f32_e32 v44, v119, v67
	s_waitcnt lgkmcnt(2)
	v_fmac_f32_e32 v44, v120, v68
	v_fmac_f32_e32 v44, v121, v69
	v_fmac_f32_e32 v44, v122, v70
	v_fmac_f32_e32 v44, v123, v71
	s_waitcnt lgkmcnt(1)
	v_fmac_f32_e32 v44, v124, v72
	v_fmac_f32_e32 v44, v125, v73
	v_fmac_f32_e32 v44, v126, v74
	v_fmac_f32_e32 v44, v127, v75
	s_waitcnt lgkmcnt(0)
	v_fmac_f32_e32 v44, v128, v76
	v_fmac_f32_e32 v44, v129, v77
	v_fmac_f32_e32 v44, v130, v78
	v_fmac_f32_e32 v44, v131, v79
	v_min_f32_e32 v132, 0, v44
	v_mul_f32_e64 v44, |v44|, s52
	v_exp_f32_e32 v44, v44
	s_nop 0
	v_add_f32_e32 v44, 1.0, v44
	v_log_f32_e32 v44, v44
	s_nop 0
	v_mul_f32_e32 v133, 0x3f317217, v44
	v_fma_f32 v133, v44, s53, -v133
	v_fmac_f32_e32 v133, 0x3377d1cf, v44
	v_fmac_f32_e32 v133, 0x3f317217, v44
	v_sub_f32_e32 v44, v132, v133
	v_mul_f32_e32 v44, 0x3d800000, v44
	ds_read_b128 v[116:119], v12 offset:1664
	ds_read_b128 v[120:123], v12 offset:1680
	ds_read_b128 v[124:127], v12 offset:1696
	ds_read_b128 v[128:131], v12 offset:1712
	v_mov_b32_e32 v45, v80
	s_waitcnt lgkmcnt(3)
; DEVINL float logsig(float z) { return fminf(z, 0.f) - __logf(1.f + __expf(-fabsf(z))); }
; DEVINL void gla_prep_unit(const Params& p, int unit) {
;     ...
;     for (int i = 0; i < 64; ++i) {
;       float z = bias;
; #pragma unroll
;       for (int r = 0; r < 16; ++r) z += afab[i * 32 + dir * 16 + r] * u[r];
;       Gc[i * 128] = logsig(z) * (1.f / 16.f);
	v_fmac_f32_e32 v45, v116, v64
	v_fmac_f32_e32 v45, v117, v65
	v_fmac_f32_e32 v45, v118, v66
	v_fmac_f32_e32 v45, v119, v67
	s_waitcnt lgkmcnt(2)
	v_fmac_f32_e32 v45, v120, v68
	v_fmac_f32_e32 v45, v121, v69
	v_fmac_f32_e32 v45, v122, v70
	v_fmac_f32_e32 v45, v123, v71
	s_waitcnt lgkmcnt(1)
	v_fmac_f32_e32 v45, v124, v72
	v_fmac_f32_e32 v45, v125, v73
	v_fmac_f32_e32 v45, v126, v74
	v_fmac_f32_e32 v45, v127, v75
	s_waitcnt lgkmcnt(0)
	v_fmac_f32_e32 v45, v128, v76
	v_fmac_f32_e32 v45, v129, v77
	v_fmac_f32_e32 v45, v130, v78
	v_fmac_f32_e32 v45, v131, v79
	v_min_f32_e32 v132, 0, v45
	v_mul_f32_e64 v45, |v45|, s52
	v_exp_f32_e32 v45, v45
	s_nop 0
	v_add_f32_e32 v45, 1.0, v45
	v_log_f32_e32 v45, v45
	s_nop 0
	v_mul_f32_e32 v133, 0x3f317217, v45
	v_fma_f32 v133, v45, s53, -v133
	v_fmac_f32_e32 v133, 0x3377d1cf, v45
	v_fmac_f32_e32 v133, 0x3f317217, v45
	v_sub_f32_e32 v45, v132, v133
	v_mul_f32_e32 v45, 0x3d800000, v45
	ds_read_b128 v[116:119], v12 offset:1792
	ds_read_b128 v[120:123], v12 offset:1808
	ds_read_b128 v[124:127], v12 offset:1824
	ds_read_b128 v[128:131], v12 offset:1840
	v_mov_b32_e32 v46, v80
	s_waitcnt lgkmcnt(3)
	v_fmac_f32_e32 v46, v116, v64
	v_fmac_f32_e32 v46, v117, v65
	v_fmac_f32_e32 v46, v118, v66
	v_fmac_f32_e32 v46, v119, v67
	s_waitcnt lgkmcnt(2)
	v_fmac_f32_e32 v46, v120, v68
	v_fmac_f32_e32 v46, v121, v69
	v_fmac_f32_e32 v46, v122, v70
	v_fmac_f32_e32 v46, v123, v71
	s_waitcnt lgkmcnt(1)
	v_fmac_f32_e32 v46, v124, v72
	v_fmac_f32_e32 v46, v125, v73
	v_fmac_f32_e32 v46, v126, v74
	v_fmac_f32_e32 v46, v127, v75
	s_waitcnt lgkmcnt(0)
	v_fmac_f32_e32 v46, v128, v76
	v_fmac_f32_e32 v46, v129, v77
	v_fmac_f32_e32 v46, v130, v78
	v_fmac_f32_e32 v46, v131, v79
	v_min_f32_e32 v132, 0, v46
	v_mul_f32_e64 v46, |v46|, s52
	v_exp_f32_e32 v46, v46
	s_nop 0
	v_add_f32_e32 v46, 1.0, v46
	v_log_f32_e32 v46, v46
	s_nop 0
	v_mul_f32_e32 v133, 0x3f317217, v46
	v_fma_f32 v133, v46, s53, -v133
	v_fmac_f32_e32 v133, 0x3377d1cf, v46
	v_fmac_f32_e32 v133, 0x3f317217, v46
	v_sub_f32_e32 v46, v132, v133
	v_mul_f32_e32 v46, 0x3d800000, v46
	ds_read_b128 v[116:119], v12 offset:1920
	ds_read_b128 v[120:123], v12 offset:1936
	ds_read_b128 v[124:127], v12 offset:1952
	ds_read_b128 v[128:131], v12 offset:1968
	v_mov_b32_e32 v47, v80
	s_waitcnt lgkmcnt(3)
	v_fmac_f32_e32 v47, v116, v64
	v_fmac_f32_e32 v47, v117, v65
	v_fmac_f32_e32 v47, v118, v66
	v_fmac_f32_e32 v47, v119, v67
	s_waitcnt lgkmcnt(2)
	v_fmac_f32_e32 v47, v120, v68
	v_fmac_f32_e32 v47, v121, v69
	v_fmac_f32_e32 v47, v122, v70
	v_fmac_f32_e32 v47, v123, v71
	s_waitcnt lgkmcnt(1)
	v_fmac_f32_e32 v47, v124, v72
	v_fmac_f32_e32 v47, v125, v73
	v_fmac_f32_e32 v47, v126, v74
	v_fmac_f32_e32 v47, v127, v75
	s_waitcnt lgkmcnt(0)
	v_fmac_f32_e32 v47, v128, v76
	v_fmac_f32_e32 v47, v129, v77
	v_fmac_f32_e32 v47, v130, v78
	v_fmac_f32_e32 v47, v131, v79
	v_min_f32_e32 v132, 0, v47
	v_mul_f32_e64 v47, |v47|, s52
	v_exp_f32_e32 v47, v47
	s_nop 0
	v_add_f32_e32 v47, 1.0, v47
	v_log_f32_e32 v47, v47
	s_nop 0
	v_mul_f32_e32 v133, 0x3f317217, v47
	v_fma_f32 v133, v47, s53, -v133
	v_fmac_f32_e32 v133, 0x3377d1cf, v47
	v_fmac_f32_e32 v133, 0x3f317217, v47
	v_sub_f32_e32 v47, v132, v133
	v_mul_f32_e32 v47, 0x3d800000, v47
	ds_read_b128 v[116:119], v12 offset:2048
	ds_read_b128 v[120:123], v12 offset:2064
	ds_read_b128 v[124:127], v12 offset:2080
	ds_read_b128 v[128:131], v12 offset:2096
	v_mov_b32_e32 v48, v80
	s_waitcnt lgkmcnt(3)
	v_fmac_f32_e32 v48, v116, v64
	v_fmac_f32_e32 v48, v117, v65
	v_fmac_f32_e32 v48, v118, v66
	v_fmac_f32_e32 v48, v119, v67
	s_waitcnt lgkmcnt(2)
	v_fmac_f32_e32 v48, v120, v68
	v_fmac_f32_e32 v48, v121, v69
	v_fmac_f32_e32 v48, v122, v70
	v_fmac_f32_e32 v48, v123, v71
	s_waitcnt lgkmcnt(1)
	v_fmac_f32_e32 v48, v124, v72
	v_fmac_f32_e32 v48, v125, v73
	v_fmac_f32_e32 v48, v126, v74
	v_fmac_f32_e32 v48, v127, v75
	s_waitcnt lgkmcnt(0)
	v_fmac_f32_e32 v48, v128, v76
	v_fmac_f32_e32 v48, v129, v77
	v_fmac_f32_e32 v48, v130, v78
	v_fmac_f32_e32 v48, v131, v79
	v_min_f32_e32 v132, 0, v48
	v_mul_f32_e64 v48, |v48|, s52
	v_exp_f32_e32 v48, v48
	s_nop 0
	v_add_f32_e32 v48, 1.0, v48
	v_log_f32_e32 v48, v48
	s_nop 0
	v_mul_f32_e32 v133, 0x3f317217, v48
	v_fma_f32 v133, v48, s53, -v133
	v_fmac_f32_e32 v133, 0x3377d1cf, v48
	v_fmac_f32_e32 v133, 0x3f317217, v48
	v_sub_f32_e32 v48, v132, v133
	v_mul_f32_e32 v48, 0x3d800000, v48
	ds_read_b128 v[116:119], v12 offset:2176
	ds_read_b128 v[120:123], v12 offset:2192
	ds_read_b128 v[124:127], v12 offset:2208
	ds_read_b128 v[128:131], v12 offset:2224
	v_mov_b32_e32 v49, v80
	s_waitcnt lgkmcnt(3)
	v_fmac_f32_e32 v49, v116, v64
	v_fmac_f32_e32 v49, v117, v65
	v_fmac_f32_e32 v49, v118, v66
	v_fmac_f32_e32 v49, v119, v67
	s_waitcnt lgkmcnt(2)
	v_fmac_f32_e32 v49, v120, v68
	v_fmac_f32_e32 v49, v121, v69
	v_fmac_f32_e32 v49, v122, v70
	v_fmac_f32_e32 v49, v123, v71
	s_waitcnt lgkmcnt(1)
	v_fmac_f32_e32 v49, v124, v72
	v_fmac_f32_e32 v49, v125, v73
	v_fmac_f32_e32 v49, v126, v74
	v_fmac_f32_e32 v49, v127, v75
	s_waitcnt lgkmcnt(0)
	v_fmac_f32_e32 v49, v128, v76
	v_fmac_f32_e32 v49, v129, v77
	v_fmac_f32_e32 v49, v130, v78
	v_fmac_f32_e32 v49, v131, v79
	v_min_f32_e32 v132, 0, v49
	v_mul_f32_e64 v49, |v49|, s52
	v_exp_f32_e32 v49, v49
	s_nop 0
	v_add_f32_e32 v49, 1.0, v49
	v_log_f32_e32 v49, v49
	s_nop 0
	v_mul_f32_e32 v133, 0x3f317217, v49
	v_fma_f32 v133, v49, s53, -v133
	v_fmac_f32_e32 v133, 0x3377d1cf, v49
	v_fmac_f32_e32 v133, 0x3f317217, v49
	v_sub_f32_e32 v49, v132, v133
	v_mul_f32_e32 v49, 0x3d800000, v49
	ds_read_b128 v[116:119], v12 offset:2304
	ds_read_b128 v[120:123], v12 offset:2320
	ds_read_b128 v[124:127], v12 offset:2336
	ds_read_b128 v[128:131], v12 offset:2352
	v_mov_b32_e32 v50, v80
	s_waitcnt lgkmcnt(3)
; DEVINL float logsig(float z) { return fminf(z, 0.f) - __logf(1.f + __expf(-fabsf(z))); }
; DEVINL void gla_prep_unit(const Params& p, int unit) {
;     ...
;     for (int i = 0; i < 64; ++i) {
;       float z = bias;
; #pragma unroll
;       for (int r = 0; r < 16; ++r) z += afab[i * 32 + dir * 16 + r] * u[r];
;       Gc[i * 128] = logsig(z) * (1.f / 16.f);
	v_fmac_f32_e32 v50, v116, v64
	v_fmac_f32_e32 v50, v117, v65
	v_fmac_f32_e32 v50, v118, v66
	v_fmac_f32_e32 v50, v119, v67
	s_waitcnt lgkmcnt(2)
	v_fmac_f32_e32 v50, v120, v68
	v_fmac_f32_e32 v50, v121, v69
	v_fmac_f32_e32 v50, v122, v70
	v_fmac_f32_e32 v50, v123, v71
	s_waitcnt lgkmcnt(1)
	v_fmac_f32_e32 v50, v124, v72
	v_fmac_f32_e32 v50, v125, v73
	v_fmac_f32_e32 v50, v126, v74
	v_fmac_f32_e32 v50, v127, v75
	s_waitcnt lgkmcnt(0)
	v_fmac_f32_e32 v50, v128, v76
	v_fmac_f32_e32 v50, v129, v77
	v_fmac_f32_e32 v50, v130, v78
	v_fmac_f32_e32 v50, v131, v79
	v_min_f32_e32 v132, 0, v50
	v_mul_f32_e64 v50, |v50|, s52
	v_exp_f32_e32 v50, v50
	s_nop 0
	v_add_f32_e32 v50, 1.0, v50
	v_log_f32_e32 v50, v50
	s_nop 0
	v_mul_f32_e32 v133, 0x3f317217, v50
	v_fma_f32 v133, v50, s53, -v133
	v_fmac_f32_e32 v133, 0x3377d1cf, v50
	v_fmac_f32_e32 v133, 0x3f317217, v50
	v_sub_f32_e32 v50, v132, v133
	v_mul_f32_e32 v50, 0x3d800000, v50
	ds_read_b128 v[116:119], v12 offset:2432
	ds_read_b128 v[120:123], v12 offset:2448
	ds_read_b128 v[124:127], v12 offset:2464
	ds_read_b128 v[128:131], v12 offset:2480
	v_mov_b32_e32 v51, v80
	s_waitcnt lgkmcnt(3)
	v_fmac_f32_e32 v51, v116, v64
	v_fmac_f32_e32 v51, v117, v65
	v_fmac_f32_e32 v51, v118, v66
	v_fmac_f32_e32 v51, v119, v67
	s_waitcnt lgkmcnt(2)
	v_fmac_f32_e32 v51, v120, v68
	v_fmac_f32_e32 v51, v121, v69
	v_fmac_f32_e32 v51, v122, v70
	v_fmac_f32_e32 v51, v123, v71
	s_waitcnt lgkmcnt(1)
	v_fmac_f32_e32 v51, v124, v72
	v_fmac_f32_e32 v51, v125, v73
	v_fmac_f32_e32 v51, v126, v74
	v_fmac_f32_e32 v51, v127, v75
	s_waitcnt lgkmcnt(0)
	v_fmac_f32_e32 v51, v128, v76
	v_fmac_f32_e32 v51, v129, v77
	v_fmac_f32_e32 v51, v130, v78
	v_fmac_f32_e32 v51, v131, v79
	v_min_f32_e32 v132, 0, v51
	v_mul_f32_e64 v51, |v51|, s52
	v_exp_f32_e32 v51, v51
	s_nop 0
	v_add_f32_e32 v51, 1.0, v51
	v_log_f32_e32 v51, v51
	s_nop 0
	v_mul_f32_e32 v133, 0x3f317217, v51
	v_fma_f32 v133, v51, s53, -v133
	v_fmac_f32_e32 v133, 0x3377d1cf, v51
	v_fmac_f32_e32 v133, 0x3f317217, v51
	v_sub_f32_e32 v51, v132, v133
	v_mul_f32_e32 v51, 0x3d800000, v51
	ds_read_b128 v[116:119], v12 offset:2560
	ds_read_b128 v[120:123], v12 offset:2576
	ds_read_b128 v[124:127], v12 offset:2592
	ds_read_b128 v[128:131], v12 offset:2608
	v_mov_b32_e32 v52, v80
	s_waitcnt lgkmcnt(3)
	v_fmac_f32_e32 v52, v116, v64
	v_fmac_f32_e32 v52, v117, v65
	v_fmac_f32_e32 v52, v118, v66
	v_fmac_f32_e32 v52, v119, v67
	s_waitcnt lgkmcnt(2)
	v_fmac_f32_e32 v52, v120, v68
	v_fmac_f32_e32 v52, v121, v69
	v_fmac_f32_e32 v52, v122, v70
	v_fmac_f32_e32 v52, v123, v71
	s_waitcnt lgkmcnt(1)
	v_fmac_f32_e32 v52, v124, v72
	v_fmac_f32_e32 v52, v125, v73
	v_fmac_f32_e32 v52, v126, v74
	v_fmac_f32_e32 v52, v127, v75
	s_waitcnt lgkmcnt(0)
	v_fmac_f32_e32 v52, v128, v76
	v_fmac_f32_e32 v52, v129, v77
	v_fmac_f32_e32 v52, v130, v78
	v_fmac_f32_e32 v52, v131, v79
	v_min_f32_e32 v132, 0, v52
	v_mul_f32_e64 v52, |v52|, s52
	v_exp_f32_e32 v52, v52
	s_nop 0
	v_add_f32_e32 v52, 1.0, v52
	v_log_f32_e32 v52, v52
	s_nop 0
	v_mul_f32_e32 v133, 0x3f317217, v52
	v_fma_f32 v133, v52, s53, -v133
	v_fmac_f32_e32 v133, 0x3377d1cf, v52
	v_fmac_f32_e32 v133, 0x3f317217, v52
	v_sub_f32_e32 v52, v132, v133
	v_mul_f32_e32 v52, 0x3d800000, v52
	ds_read_b128 v[116:119], v12 offset:2688
	ds_read_b128 v[120:123], v12 offset:2704
	ds_read_b128 v[124:127], v12 offset:2720
	ds_read_b128 v[128:131], v12 offset:2736
	v_mov_b32_e32 v53, v80
	s_waitcnt lgkmcnt(3)
	v_fmac_f32_e32 v53, v116, v64
	v_fmac_f32_e32 v53, v117, v65
	v_fmac_f32_e32 v53, v118, v66
	v_fmac_f32_e32 v53, v119, v67
	s_waitcnt lgkmcnt(2)
	v_fmac_f32_e32 v53, v120, v68
	v_fmac_f32_e32 v53, v121, v69
	v_fmac_f32_e32 v53, v122, v70
	v_fmac_f32_e32 v53, v123, v71
	s_waitcnt lgkmcnt(1)
	v_fmac_f32_e32 v53, v124, v72
	v_fmac_f32_e32 v53, v125, v73
	v_fmac_f32_e32 v53, v126, v74
	v_fmac_f32_e32 v53, v127, v75
	s_waitcnt lgkmcnt(0)
	v_fmac_f32_e32 v53, v128, v76
	v_fmac_f32_e32 v53, v129, v77
	v_fmac_f32_e32 v53, v130, v78
	v_fmac_f32_e32 v53, v131, v79
	v_min_f32_e32 v132, 0, v53
	v_mul_f32_e64 v53, |v53|, s52
	v_exp_f32_e32 v53, v53
	s_nop 0
	v_add_f32_e32 v53, 1.0, v53
	v_log_f32_e32 v53, v53
	s_nop 0
	v_mul_f32_e32 v133, 0x3f317217, v53
	v_fma_f32 v133, v53, s53, -v133
	v_fmac_f32_e32 v133, 0x3377d1cf, v53
	v_fmac_f32_e32 v133, 0x3f317217, v53
	v_sub_f32_e32 v53, v132, v133
	v_mul_f32_e32 v53, 0x3d800000, v53
	ds_read_b128 v[116:119], v12 offset:2816
	ds_read_b128 v[120:123], v12 offset:2832
	ds_read_b128 v[124:127], v12 offset:2848
	ds_read_b128 v[128:131], v12 offset:2864
	v_mov_b32_e32 v54, v80
	s_waitcnt lgkmcnt(3)
	v_fmac_f32_e32 v54, v116, v64
	v_fmac_f32_e32 v54, v117, v65
	v_fmac_f32_e32 v54, v118, v66
	v_fmac_f32_e32 v54, v119, v67
	s_waitcnt lgkmcnt(2)
	v_fmac_f32_e32 v54, v120, v68
	v_fmac_f32_e32 v54, v121, v69
	v_fmac_f32_e32 v54, v122, v70
	v_fmac_f32_e32 v54, v123, v71
	s_waitcnt lgkmcnt(1)
	v_fmac_f32_e32 v54, v124, v72
	v_fmac_f32_e32 v54, v125, v73
	v_fmac_f32_e32 v54, v126, v74
	v_fmac_f32_e32 v54, v127, v75
	s_waitcnt lgkmcnt(0)
	v_fmac_f32_e32 v54, v128, v76
	v_fmac_f32_e32 v54, v129, v77
	v_fmac_f32_e32 v54, v130, v78
	v_fmac_f32_e32 v54, v131, v79
	v_min_f32_e32 v132, 0, v54
	v_mul_f32_e64 v54, |v54|, s52
	v_exp_f32_e32 v54, v54
	s_nop 0
	v_add_f32_e32 v54, 1.0, v54
	v_log_f32_e32 v54, v54
	s_nop 0
	v_mul_f32_e32 v133, 0x3f317217, v54
	v_fma_f32 v133, v54, s53, -v133
	v_fmac_f32_e32 v133, 0x3377d1cf, v54
	v_fmac_f32_e32 v133, 0x3f317217, v54
	v_sub_f32_e32 v54, v132, v133
	v_mul_f32_e32 v54, 0x3d800000, v54
	ds_read_b128 v[116:119], v12 offset:2944
	ds_read_b128 v[120:123], v12 offset:2960
	ds_read_b128 v[124:127], v12 offset:2976
	ds_read_b128 v[128:131], v12 offset:2992
	v_mov_b32_e32 v55, v80
	s_waitcnt lgkmcnt(3)
; DEVINL float logsig(float z) { return fminf(z, 0.f) - __logf(1.f + __expf(-fabsf(z))); }
; DEVINL void gla_prep_unit(const Params& p, int unit) {
;     ...
;     for (int i = 0; i < 64; ++i) {
;       float z = bias;
; #pragma unroll
;       for (int r = 0; r < 16; ++r) z += afab[i * 32 + dir * 16 + r] * u[r];
;       Gc[i * 128] = logsig(z) * (1.f / 16.f);
	v_fmac_f32_e32 v55, v116, v64
	v_fmac_f32_e32 v55, v117, v65
	v_fmac_f32_e32 v55, v118, v66
	v_fmac_f32_e32 v55, v119, v67
	s_waitcnt lgkmcnt(2)
	v_fmac_f32_e32 v55, v120, v68
	v_fmac_f32_e32 v55, v121, v69
	v_fmac_f32_e32 v55, v122, v70
	v_fmac_f32_e32 v55, v123, v71
	s_waitcnt lgkmcnt(1)
	v_fmac_f32_e32 v55, v124, v72
	v_fmac_f32_e32 v55, v125, v73
	v_fmac_f32_e32 v55, v126, v74
	v_fmac_f32_e32 v55, v127, v75
	s_waitcnt lgkmcnt(0)
	v_fmac_f32_e32 v55, v128, v76
	v_fmac_f32_e32 v55, v129, v77
	v_fmac_f32_e32 v55, v130, v78
	v_fmac_f32_e32 v55, v131, v79
	v_min_f32_e32 v132, 0, v55
	v_mul_f32_e64 v55, |v55|, s52
	v_exp_f32_e32 v55, v55
	s_nop 0
	v_add_f32_e32 v55, 1.0, v55
	v_log_f32_e32 v55, v55
	s_nop 0
	v_mul_f32_e32 v133, 0x3f317217, v55
	v_fma_f32 v133, v55, s53, -v133
	v_fmac_f32_e32 v133, 0x3377d1cf, v55
	v_fmac_f32_e32 v133, 0x3f317217, v55
	v_sub_f32_e32 v55, v132, v133
	v_mul_f32_e32 v55, 0x3d800000, v55
	ds_read_b128 v[116:119], v12 offset:3072
	ds_read_b128 v[120:123], v12 offset:3088
	ds_read_b128 v[124:127], v12 offset:3104
	ds_read_b128 v[128:131], v12 offset:3120
	v_mov_b32_e32 v56, v80
	s_waitcnt lgkmcnt(3)
	v_fmac_f32_e32 v56, v116, v64
	v_fmac_f32_e32 v56, v117, v65
	v_fmac_f32_e32 v56, v118, v66
	v_fmac_f32_e32 v56, v119, v67
	s_waitcnt lgkmcnt(2)
	v_fmac_f32_e32 v56, v120, v68
	v_fmac_f32_e32 v56, v121, v69
	v_fmac_f32_e32 v56, v122, v70
	v_fmac_f32_e32 v56, v123, v71
	s_waitcnt lgkmcnt(1)
	v_fmac_f32_e32 v56, v124, v72
	v_fmac_f32_e32 v56, v125, v73
	v_fmac_f32_e32 v56, v126, v74
	v_fmac_f32_e32 v56, v127, v75
	s_waitcnt lgkmcnt(0)
	v_fmac_f32_e32 v56, v128, v76
	v_fmac_f32_e32 v56, v129, v77
	v_fmac_f32_e32 v56, v130, v78
	v_fmac_f32_e32 v56, v131, v79
	v_min_f32_e32 v132, 0, v56
	v_mul_f32_e64 v56, |v56|, s52
	v_exp_f32_e32 v56, v56
	s_nop 0
	v_add_f32_e32 v56, 1.0, v56
	v_log_f32_e32 v56, v56
	s_nop 0
	v_mul_f32_e32 v133, 0x3f317217, v56
	v_fma_f32 v133, v56, s53, -v133
	v_fmac_f32_e32 v133, 0x3377d1cf, v56
	v_fmac_f32_e32 v133, 0x3f317217, v56
	v_sub_f32_e32 v56, v132, v133
	v_mul_f32_e32 v56, 0x3d800000, v56
	ds_read_b128 v[116:119], v12 offset:3200
	ds_read_b128 v[120:123], v12 offset:3216
	ds_read_b128 v[124:127], v12 offset:3232
	ds_read_b128 v[128:131], v12 offset:3248
	v_mov_b32_e32 v57, v80
	s_waitcnt lgkmcnt(3)
	v_fmac_f32_e32 v57, v116, v64
	v_fmac_f32_e32 v57, v117, v65
	v_fmac_f32_e32 v57, v118, v66
	v_fmac_f32_e32 v57, v119, v67
	s_waitcnt lgkmcnt(2)
	v_fmac_f32_e32 v57, v120, v68
	v_fmac_f32_e32 v57, v121, v69
	v_fmac_f32_e32 v57, v122, v70
	v_fmac_f32_e32 v57, v123, v71
	s_waitcnt lgkmcnt(1)
	v_fmac_f32_e32 v57, v124, v72
	v_fmac_f32_e32 v57, v125, v73
	v_fmac_f32_e32 v57, v126, v74
	v_fmac_f32_e32 v57, v127, v75
	s_waitcnt lgkmcnt(0)
	v_fmac_f32_e32 v57, v128, v76
	v_fmac_f32_e32 v57, v129, v77
	v_fmac_f32_e32 v57, v130, v78
	v_fmac_f32_e32 v57, v131, v79
	v_min_f32_e32 v132, 0, v57
	v_mul_f32_e64 v57, |v57|, s52
	v_exp_f32_e32 v57, v57
	s_nop 0
	v_add_f32_e32 v57, 1.0, v57
	v_log_f32_e32 v57, v57
	s_nop 0
	v_mul_f32_e32 v133, 0x3f317217, v57
	v_fma_f32 v133, v57, s53, -v133
	v_fmac_f32_e32 v133, 0x3377d1cf, v57
	v_fmac_f32_e32 v133, 0x3f317217, v57
	v_sub_f32_e32 v57, v132, v133
	v_mul_f32_e32 v57, 0x3d800000, v57
	ds_read_b128 v[116:119], v12 offset:3328
	ds_read_b128 v[120:123], v12 offset:3344
	ds_read_b128 v[124:127], v12 offset:3360
	ds_read_b128 v[128:131], v12 offset:3376
	v_mov_b32_e32 v58, v80
	s_waitcnt lgkmcnt(3)
	v_fmac_f32_e32 v58, v116, v64
	v_fmac_f32_e32 v58, v117, v65
	v_fmac_f32_e32 v58, v118, v66
	v_fmac_f32_e32 v58, v119, v67
	s_waitcnt lgkmcnt(2)
	v_fmac_f32_e32 v58, v120, v68
	v_fmac_f32_e32 v58, v121, v69
	v_fmac_f32_e32 v58, v122, v70
	v_fmac_f32_e32 v58, v123, v71
	s_waitcnt lgkmcnt(1)
	v_fmac_f32_e32 v58, v124, v72
	v_fmac_f32_e32 v58, v125, v73
	v_fmac_f32_e32 v58, v126, v74
	v_fmac_f32_e32 v58, v127, v75
	s_waitcnt lgkmcnt(0)
	v_fmac_f32_e32 v58, v128, v76
	v_fmac_f32_e32 v58, v129, v77
	v_fmac_f32_e32 v58, v130, v78
	v_fmac_f32_e32 v58, v131, v79
	v_min_f32_e32 v132, 0, v58
	v_mul_f32_e64 v58, |v58|, s52
	v_exp_f32_e32 v58, v58
	s_nop 0
	v_add_f32_e32 v58, 1.0, v58
	v_log_f32_e32 v58, v58
	s_nop 0
	v_mul_f32_e32 v133, 0x3f317217, v58
	v_fma_f32 v133, v58, s53, -v133
	v_fmac_f32_e32 v133, 0x3377d1cf, v58
	v_fmac_f32_e32 v133, 0x3f317217, v58
	v_sub_f32_e32 v58, v132, v133
	v_mul_f32_e32 v58, 0x3d800000, v58
	ds_read_b128 v[116:119], v12 offset:3456
	ds_read_b128 v[120:123], v12 offset:3472
	ds_read_b128 v[124:127], v12 offset:3488
	ds_read_b128 v[128:131], v12 offset:3504
	v_mov_b32_e32 v59, v80
	s_waitcnt lgkmcnt(3)
	v_fmac_f32_e32 v59, v116, v64
	v_fmac_f32_e32 v59, v117, v65
	v_fmac_f32_e32 v59, v118, v66
	v_fmac_f32_e32 v59, v119, v67
	s_waitcnt lgkmcnt(2)
	v_fmac_f32_e32 v59, v120, v68
	v_fmac_f32_e32 v59, v121, v69
	v_fmac_f32_e32 v59, v122, v70
	v_fmac_f32_e32 v59, v123, v71
	s_waitcnt lgkmcnt(1)
	v_fmac_f32_e32 v59, v124, v72
	v_fmac_f32_e32 v59, v125, v73
	v_fmac_f32_e32 v59, v126, v74
	v_fmac_f32_e32 v59, v127, v75
	s_waitcnt lgkmcnt(0)
	v_fmac_f32_e32 v59, v128, v76
	v_fmac_f32_e32 v59, v129, v77
	v_fmac_f32_e32 v59, v130, v78
	v_fmac_f32_e32 v59, v131, v79
	v_min_f32_e32 v132, 0, v59
	v_mul_f32_e64 v59, |v59|, s52
	v_exp_f32_e32 v59, v59
	s_nop 0
	v_add_f32_e32 v59, 1.0, v59
	v_log_f32_e32 v59, v59
	s_nop 0
	v_mul_f32_e32 v133, 0x3f317217, v59
	v_fma_f32 v133, v59, s53, -v133
	v_fmac_f32_e32 v133, 0x3377d1cf, v59
	v_fmac_f32_e32 v133, 0x3f317217, v59
	v_sub_f32_e32 v59, v132, v133
	v_mul_f32_e32 v59, 0x3d800000, v59
	ds_read_b128 v[116:119], v12 offset:3584
	ds_read_b128 v[120:123], v12 offset:3600
	ds_read_b128 v[124:127], v12 offset:3616
	ds_read_b128 v[128:131], v12 offset:3632
	v_mov_b32_e32 v60, v80
	s_waitcnt lgkmcnt(3)
; DEVINL float logsig(float z) { return fminf(z, 0.f) - __logf(1.f + __expf(-fabsf(z))); }
; DEVINL void gla_prep_unit(const Params& p, int unit) {
;     ...
;     for (int i = 0; i < 64; ++i) {
;       float z = bias;
; #pragma unroll
;       for (int r = 0; r < 16; ++r) z += afab[i * 32 + dir * 16 + r] * u[r];
;       Gc[i * 128] = logsig(z) * (1.f / 16.f);
;     }
;     float run = 0.f;
;     if (dir == 0) { for (int i = 0; i < 64; ++i) { run += Gc[i * 128]; Gc[i * 128] = run; } }
;     else { for (int i = 63; i >= 0; --i) { run += Gc[i * 128]; Gc[i * 128] = run; } }
	v_fmac_f32_e32 v60, v116, v64
	v_fmac_f32_e32 v60, v117, v65
	v_fmac_f32_e32 v60, v118, v66
	v_fmac_f32_e32 v60, v119, v67
	s_waitcnt lgkmcnt(2)
	v_fmac_f32_e32 v60, v120, v68
	v_fmac_f32_e32 v60, v121, v69
	v_fmac_f32_e32 v60, v122, v70
	v_fmac_f32_e32 v60, v123, v71
	s_waitcnt lgkmcnt(1)
	v_fmac_f32_e32 v60, v124, v72
	v_fmac_f32_e32 v60, v125, v73
	v_fmac_f32_e32 v60, v126, v74
	v_fmac_f32_e32 v60, v127, v75
	s_waitcnt lgkmcnt(0)
	v_fmac_f32_e32 v60, v128, v76
	v_fmac_f32_e32 v60, v129, v77
	v_fmac_f32_e32 v60, v130, v78
	v_fmac_f32_e32 v60, v131, v79
	v_min_f32_e32 v132, 0, v60
	v_mul_f32_e64 v60, |v60|, s52
	v_exp_f32_e32 v60, v60
	s_nop 0
	v_add_f32_e32 v60, 1.0, v60
	v_log_f32_e32 v60, v60
	s_nop 0
	v_mul_f32_e32 v133, 0x3f317217, v60
	v_fma_f32 v133, v60, s53, -v133
	v_fmac_f32_e32 v133, 0x3377d1cf, v60
	v_fmac_f32_e32 v133, 0x3f317217, v60
	v_sub_f32_e32 v60, v132, v133
	v_mul_f32_e32 v60, 0x3d800000, v60
	ds_read_b128 v[116:119], v12 offset:3712
	ds_read_b128 v[120:123], v12 offset:3728
	ds_read_b128 v[124:127], v12 offset:3744
	ds_read_b128 v[128:131], v12 offset:3760
	v_mov_b32_e32 v61, v80
	s_waitcnt lgkmcnt(3)
	v_fmac_f32_e32 v61, v116, v64
	v_fmac_f32_e32 v61, v117, v65
	v_fmac_f32_e32 v61, v118, v66
	v_fmac_f32_e32 v61, v119, v67
	s_waitcnt lgkmcnt(2)
	v_fmac_f32_e32 v61, v120, v68
	v_fmac_f32_e32 v61, v121, v69
	v_fmac_f32_e32 v61, v122, v70
	v_fmac_f32_e32 v61, v123, v71
	s_waitcnt lgkmcnt(1)
	v_fmac_f32_e32 v61, v124, v72
	v_fmac_f32_e32 v61, v125, v73
	v_fmac_f32_e32 v61, v126, v74
	v_fmac_f32_e32 v61, v127, v75
	s_waitcnt lgkmcnt(0)
	v_fmac_f32_e32 v61, v128, v76
	v_fmac_f32_e32 v61, v129, v77
	v_fmac_f32_e32 v61, v130, v78
	v_fmac_f32_e32 v61, v131, v79
	v_min_f32_e32 v132, 0, v61
	v_mul_f32_e64 v61, |v61|, s52
	v_exp_f32_e32 v61, v61
	s_nop 0
	v_add_f32_e32 v61, 1.0, v61
	v_log_f32_e32 v61, v61
	s_nop 0
	v_mul_f32_e32 v133, 0x3f317217, v61
	v_fma_f32 v133, v61, s53, -v133
	v_fmac_f32_e32 v133, 0x3377d1cf, v61
	v_fmac_f32_e32 v133, 0x3f317217, v61
	v_sub_f32_e32 v61, v132, v133
	v_mul_f32_e32 v61, 0x3d800000, v61
	ds_read_b128 v[116:119], v12 offset:3840
	ds_read_b128 v[120:123], v12 offset:3856
	ds_read_b128 v[124:127], v12 offset:3872
	ds_read_b128 v[128:131], v12 offset:3888
	v_mov_b32_e32 v62, v80
	s_waitcnt lgkmcnt(3)
	v_fmac_f32_e32 v62, v116, v64
	v_fmac_f32_e32 v62, v117, v65
	v_fmac_f32_e32 v62, v118, v66
	v_fmac_f32_e32 v62, v119, v67
	s_waitcnt lgkmcnt(2)
	v_fmac_f32_e32 v62, v120, v68
	v_fmac_f32_e32 v62, v121, v69
	v_fmac_f32_e32 v62, v122, v70
	v_fmac_f32_e32 v62, v123, v71
	s_waitcnt lgkmcnt(1)
	v_fmac_f32_e32 v62, v124, v72
	v_fmac_f32_e32 v62, v125, v73
	v_fmac_f32_e32 v62, v126, v74
	v_fmac_f32_e32 v62, v127, v75
	s_waitcnt lgkmcnt(0)
	v_fmac_f32_e32 v62, v128, v76
	v_fmac_f32_e32 v62, v129, v77
	v_fmac_f32_e32 v62, v130, v78
	v_fmac_f32_e32 v62, v131, v79
	v_min_f32_e32 v132, 0, v62
	v_mul_f32_e64 v62, |v62|, s52
	v_exp_f32_e32 v62, v62
	s_nop 0
	v_add_f32_e32 v62, 1.0, v62
	v_log_f32_e32 v62, v62
	s_nop 0
	v_mul_f32_e32 v133, 0x3f317217, v62
	v_fma_f32 v133, v62, s53, -v133
	v_fmac_f32_e32 v133, 0x3377d1cf, v62
	v_fmac_f32_e32 v133, 0x3f317217, v62
	v_sub_f32_e32 v62, v132, v133
	v_mul_f32_e32 v62, 0x3d800000, v62
	ds_read_b128 v[116:119], v12 offset:3968
	ds_read_b128 v[120:123], v12 offset:3984
	ds_read_b128 v[124:127], v12 offset:4000
	ds_read_b128 v[128:131], v12 offset:4016
	v_mov_b32_e32 v63, v80
	s_waitcnt lgkmcnt(3)
	v_fmac_f32_e32 v63, v116, v64
	v_fmac_f32_e32 v63, v117, v65
	v_fmac_f32_e32 v63, v118, v66
	v_fmac_f32_e32 v63, v119, v67
	s_waitcnt lgkmcnt(2)
	v_fmac_f32_e32 v63, v120, v68
	v_fmac_f32_e32 v63, v121, v69
	v_fmac_f32_e32 v63, v122, v70
	v_fmac_f32_e32 v63, v123, v71
	s_waitcnt lgkmcnt(1)
	v_fmac_f32_e32 v63, v124, v72
	v_fmac_f32_e32 v63, v125, v73
	v_fmac_f32_e32 v63, v126, v74
	v_fmac_f32_e32 v63, v127, v75
	s_waitcnt lgkmcnt(0)
	v_fmac_f32_e32 v63, v128, v76
	v_fmac_f32_e32 v63, v129, v77
	v_fmac_f32_e32 v63, v130, v78
	v_fmac_f32_e32 v63, v131, v79
	v_min_f32_e32 v132, 0, v63
	v_mul_f32_e64 v63, |v63|, s52
	v_exp_f32_e32 v63, v63
	s_nop 0
	v_add_f32_e32 v63, 1.0, v63
	v_log_f32_e32 v63, v63
	s_nop 0
	v_mul_f32_e32 v133, 0x3f317217, v63
	v_fma_f32 v133, v63, s53, -v133
	v_fmac_f32_e32 v133, 0x3377d1cf, v63
	v_fmac_f32_e32 v133, 0x3f317217, v63
	v_sub_f32_e32 v63, v132, v133
	v_mul_f32_e32 v63, 0x3d800000, v63
	s_cmp_eq_u32 s71, 0
	s_cbranch_scc0 .Lgl_tot_b
	v_mov_b32_e32 v134, v32
	v_add_f32_e32 v134, v134, v33
	v_add_f32_e32 v134, v134, v34
	v_add_f32_e32 v134, v134, v35
	v_add_f32_e32 v134, v134, v36
	v_add_f32_e32 v134, v134, v37
	v_add_f32_e32 v134, v134, v38
	v_add_f32_e32 v134, v134, v39
	v_add_f32_e32 v134, v134, v40
	v_add_f32_e32 v134, v134, v41
	v_add_f32_e32 v134, v134, v42
	v_add_f32_e32 v134, v134, v43
	v_add_f32_e32 v134, v134, v44
	v_add_f32_e32 v134, v134, v45
	v_add_f32_e32 v134, v134, v46
	v_add_f32_e32 v134, v134, v47
	v_add_f32_e32 v134, v134, v48
	v_add_f32_e32 v134, v134, v49
	v_add_f32_e32 v134, v134, v50
	v_add_f32_e32 v134, v134, v51
	v_add_f32_e32 v134, v134, v52
	v_add_f32_e32 v134, v134, v53
	v_add_f32_e32 v134, v134, v54
	v_add_f32_e32 v134, v134, v55
	v_add_f32_e32 v134, v134, v56
	v_add_f32_e32 v134, v134, v57
	v_add_f32_e32 v134, v134, v58
	v_add_f32_e32 v134, v134, v59
	v_add_f32_e32 v134, v134, v60
	v_add_f32_e32 v134, v134, v61
	v_add_f32_e32 v134, v134, v62
	v_add_f32_e32 v134, v134, v63
	s_branch .Lgl_tot_e

; DEVINL void gla_prep_unit(const Params& p, int unit) {
;     ...
;     float run = 0.f;
;     if (dir == 0) { for (int i = 0; i < 64; ++i) { run += Gc[i * 128]; Gc[i * 128] = run; } }
;     else { for (int i = 63; i >= 0; --i) { run += Gc[i * 128]; Gc[i * 128] = run; } }
.Lgl_carry:
	s_cmp_eq_u32 s71, 0
	s_cbranch_scc0 .Lgl_scan_b
	v_add_f32_e32 v135, v135, v32
	v_mov_b32_e32 v32, v135
	v_add_f32_e32 v135, v135, v33
	v_mov_b32_e32 v33, v135
	v_add_f32_e32 v135, v135, v34
	v_mov_b32_e32 v34, v135
	v_add_f32_e32 v135, v135, v35
	v_mov_b32_e32 v35, v135
	v_add_f32_e32 v135, v135, v36
	v_mov_b32_e32 v36, v135
	v_add_f32_e32 v135, v135, v37
	v_mov_b32_e32 v37, v135
	v_add_f32_e32 v135, v135, v38
	v_mov_b32_e32 v38, v135
	v_add_f32_e32 v135, v135, v39
	v_mov_b32_e32 v39, v135
	v_add_f32_e32 v135, v135, v40
	v_mov_b32_e32 v40, v135
	v_add_f32_e32 v135, v135, v41
	v_mov_b32_e32 v41, v135
	v_add_f32_e32 v135, v135, v42
	v_mov_b32_e32 v42, v135
	v_add_f32_e32 v135, v135, v43
	v_mov_b32_e32 v43, v135
	v_add_f32_e32 v135, v135, v44
	v_mov_b32_e32 v44, v135
	v_add_f32_e32 v135, v135, v45
	v_mov_b32_e32 v45, v135
	v_add_f32_e32 v135, v135, v46
	v_mov_b32_e32 v46, v135
	v_add_f32_e32 v135, v135, v47
	v_mov_b32_e32 v47, v135
	v_add_f32_e32 v135, v135, v48
	v_mov_b32_e32 v48, v135
	v_add_f32_e32 v135, v135, v49
	v_mov_b32_e32 v49, v135
	v_add_f32_e32 v135, v135, v50
	v_mov_b32_e32 v50, v135
	v_add_f32_e32 v135, v135, v51
	v_mov_b32_e32 v51, v135
	v_add_f32_e32 v135, v135, v52
	v_mov_b32_e32 v52, v135
	v_add_f32_e32 v135, v135, v53
	v_mov_b32_e32 v53, v135
	v_add_f32_e32 v135, v135, v54
	v_mov_b32_e32 v54, v135
	v_add_f32_e32 v135, v135, v55
	v_mov_b32_e32 v55, v135
	v_add_f32_e32 v135, v135, v56
	v_mov_b32_e32 v56, v135
	v_add_f32_e32 v135, v135, v57
	v_mov_b32_e32 v57, v135
	v_add_f32_e32 v135, v135, v58
	v_mov_b32_e32 v58, v135
	v_add_f32_e32 v135, v135, v59
	v_mov_b32_e32 v59, v135
	v_add_f32_e32 v135, v135, v60
	v_mov_b32_e32 v60, v135
	v_add_f32_e32 v135, v135, v61
	v_mov_b32_e32 v61, v135
	v_add_f32_e32 v135, v135, v62
	v_mov_b32_e32 v62, v135
	v_add_f32_e32 v135, v135, v63
	v_mov_b32_e32 v63, v135
	s_branch .Lgl_scan_e

; DEVINL u16 f2bf(float a) { return (u16)(pk2(a, 0.f) & 0xffffu); }
; DEVINL float bf2f(u16 h) { return __uint_as_float(((unsigned)h) << 16); }
; DEVINL int fragpos(int idx) { const int w = idx & 31; return (idx & ~31) + (((w & 15) >> 2) << 3) + (w & 3) + ((w >> 4) << 2); }
; DEVINL void gla_prep_unit(const Params& p, int unit) {
;     ...
;     const float bedge = run;
;     const long hb = ((long)(dir * 2 + b) * 4 + h);
;     const int pk = fragpos(kk);
;     u16* qt = (u16*)(ws + O_QT) + (hb * 4096 + c * 64) * 128 + pk;
;     u16* kt = (u16*)(ws + O_KT) + (hb * 4096 + c * 64) * 128 + pk;
;     ((float*)(ws + O_DEC))[(hb * 64 + c) * 128 + kk] = __expf(bedge);
;     u16* KDr = KD + (dir * 128 + kk) * 72;
;     const unsigned short* qsrc = cols + tok0 * NCP + C_Q + h * 128 + kk;
;     const unsigned short* ksrc = cols + tok0 * NCP + C_K + h * 128 + kk;
; #pragma unroll 1
;     for (int i0 = 0; i0 < 64; i0 += 8) {
;       u16 qv[8], kv[8];
; #pragma unroll
;       for (int j = 0; j < 8; ++j) { qv[j] = qsrc[(long)(i0 + j) * NCP]; kv[j] = ksrc[(long)(i0 + j) * NCP]; }
; #pragma unroll
;       for (int j = 0; j < 8; ++j) {
;         const int i = i0 + j;
;         float bb = Gc[i * 128];
;         float q = bf2f(qv[j]);
;         float k = bf2f(kv[j]);
;         qt[i * 128] = f2bf(q * 0.08838834764831845f * __expf(bb));
;         kt[i * 128] = f2bf(k * __expf(-bb));
;         KDr[fragpos(i)] = f2bf(k * __expf(bedge - bb));
.Lgl_noedge:
	s_waitcnt lgkmcnt(0)
	s_barrier
	ds_read_b32 v136, v15
	ds_read_u16 v192, v16 offset:0
	ds_read_u16 v193, v16 offset:256
	ds_read_u16 v194, v16 offset:512
	ds_read_u16 v195, v16 offset:768
	ds_read_u16 v196, v16 offset:1024
	ds_read_u16 v197, v16 offset:1280
	ds_read_u16 v198, v16 offset:1536
	ds_read_u16 v199, v16 offset:1792
	ds_read_u16 v200, v16 offset:2048
	ds_read_u16 v201, v16 offset:2304
	ds_read_u16 v202, v16 offset:2560
	ds_read_u16 v203, v16 offset:2816
	ds_read_u16 v204, v16 offset:3072
	ds_read_u16 v205, v16 offset:3328
	ds_read_u16 v206, v16 offset:3584
	ds_read_u16 v207, v16 offset:3840
	ds_read_u16 v208, v16 offset:4096
	ds_read_u16 v209, v16 offset:4352
	ds_read_u16 v210, v16 offset:4608
	ds_read_u16 v211, v16 offset:4864
	ds_read_u16 v212, v16 offset:5120
	ds_read_u16 v213, v16 offset:5376
	ds_read_u16 v214, v16 offset:5632
	ds_read_u16 v215, v16 offset:5888
	ds_read_u16 v216, v16 offset:6144
	ds_read_u16 v217, v16 offset:6400
	ds_read_u16 v218, v16 offset:6656
	ds_read_u16 v219, v16 offset:6912
	ds_read_u16 v220, v16 offset:7168
	ds_read_u16 v221, v16 offset:7424
	ds_read_u16 v222, v16 offset:7680
	ds_read_u16 v223, v16 offset:7936
	ds_write_b32 v17, v32 offset:0
	ds_write_b32 v17, v33 offset:512
	ds_write_b32 v17, v34 offset:1024
	ds_write_b32 v17, v35 offset:1536
	ds_write_b32 v17, v36 offset:2048
	ds_write_b32 v17, v37 offset:2560
	ds_write_b32 v17, v38 offset:3072
	ds_write_b32 v17, v39 offset:3584
	ds_write_b32 v17, v40 offset:4096
	ds_write_b32 v17, v41 offset:4608
	ds_write_b32 v17, v42 offset:5120
	ds_write_b32 v17, v43 offset:5632
	ds_write_b32 v17, v44 offset:6144
	ds_write_b32 v17, v45 offset:6656
	ds_write_b32 v17, v46 offset:7168
	ds_write_b32 v17, v47 offset:7680
	ds_write_b32 v17, v48 offset:8192
	ds_write_b32 v17, v49 offset:8704
	ds_write_b32 v17, v50 offset:9216
	ds_write_b32 v17, v51 offset:9728
	ds_write_b32 v17, v52 offset:10240
	ds_write_b32 v17, v53 offset:10752
	ds_write_b32 v17, v54 offset:11264
	ds_write_b32 v17, v55 offset:11776
	ds_write_b32 v17, v56 offset:12288
	ds_write_b32 v17, v57 offset:12800
	ds_write_b32 v17, v58 offset:13312
	ds_write_b32 v17, v59 offset:13824
	ds_write_b32 v17, v60 offset:14336
	ds_write_b32 v17, v61 offset:14848
	ds_write_b32 v17, v62 offset:15360
	ds_write_b32 v17, v63 offset:15872
	s_waitcnt lgkmcnt(15)
	s_waitcnt lgkmcnt(0)
	v_sub_f32_e32 v116, v136, v32
	v_mul_f32_e32 v116, 0x3fb8aa3b, v116
	v_exp_f32_e32 v116, v116
	v_lshlrev_b32_e32 v192, 16, v192
	v_mul_f32_e32 v192, v116, v192
	v_sub_f32_e32 v116, v136, v33
	v_mul_f32_e32 v116, 0x3fb8aa3b, v116
	v_exp_f32_e32 v116, v116
	v_lshlrev_b32_e32 v193, 16, v193
	v_mul_f32_e32 v193, v116, v193
	v_sub_f32_e32 v116, v136, v34
	v_mul_f32_e32 v116, 0x3fb8aa3b, v116
	v_exp_f32_e32 v116, v116
	v_lshlrev_b32_e32 v194, 16, v194
	v_mul_f32_e32 v194, v116, v194
	v_sub_f32_e32 v116, v136, v35
	v_mul_f32_e32 v116, 0x3fb8aa3b, v116
	v_exp_f32_e32 v116, v116
	v_lshlrev_b32_e32 v195, 16, v195
	v_mul_f32_e32 v195, v116, v195
	v_sub_f32_e32 v116, v136, v36
	v_mul_f32_e32 v116, 0x3fb8aa3b, v116
	v_exp_f32_e32 v116, v116
	v_lshlrev_b32_e32 v196, 16, v196
	v_mul_f32_e32 v196, v116, v196
	v_sub_f32_e32 v116, v136, v37
	v_mul_f32_e32 v116, 0x3fb8aa3b, v116
	v_exp_f32_e32 v116, v116
	v_lshlrev_b32_e32 v197, 16, v197
	v_mul_f32_e32 v197, v116, v197
	v_sub_f32_e32 v116, v136, v38
	v_mul_f32_e32 v116, 0x3fb8aa3b, v116
	v_exp_f32_e32 v116, v116
	v_lshlrev_b32_e32 v198, 16, v198
	v_mul_f32_e32 v198, v116, v198
	v_sub_f32_e32 v116, v136, v39
	v_mul_f32_e32 v116, 0x3fb8aa3b, v116
	v_exp_f32_e32 v116, v116
	v_lshlrev_b32_e32 v199, 16, v199
	v_mul_f32_e32 v199, v116, v199
	v_sub_f32_e32 v116, v136, v40
	v_mul_f32_e32 v116, 0x3fb8aa3b, v116
	v_exp_f32_e32 v116, v116
	v_lshlrev_b32_e32 v200, 16, v200
	v_mul_f32_e32 v200, v116, v200
	v_sub_f32_e32 v116, v136, v41
	v_mul_f32_e32 v116, 0x3fb8aa3b, v116
	v_exp_f32_e32 v116, v116
	v_lshlrev_b32_e32 v201, 16, v201
	v_mul_f32_e32 v201, v116, v201
	v_sub_f32_e32 v116, v136, v42
	v_mul_f32_e32 v116, 0x3fb8aa3b, v116
	v_exp_f32_e32 v116, v116
	v_lshlrev_b32_e32 v202, 16, v202
	v_mul_f32_e32 v202, v116, v202
	v_sub_f32_e32 v116, v136, v43
	v_mul_f32_e32 v116, 0x3fb8aa3b, v116
	v_exp_f32_e32 v116, v116
	v_lshlrev_b32_e32 v203, 16, v203
	v_mul_f32_e32 v203, v116, v203
	v_sub_f32_e32 v116, v136, v44
	v_mul_f32_e32 v116, 0x3fb8aa3b, v116
	v_exp_f32_e32 v116, v116
	v_lshlrev_b32_e32 v204, 16, v204
	v_mul_f32_e32 v204, v116, v204
	v_sub_f32_e32 v116, v136, v45
	v_mul_f32_e32 v116, 0x3fb8aa3b, v116
	v_exp_f32_e32 v116, v116
	v_lshlrev_b32_e32 v205, 16, v205
	v_mul_f32_e32 v205, v116, v205
	v_sub_f32_e32 v116, v136, v46
	v_mul_f32_e32 v116, 0x3fb8aa3b, v116
	v_exp_f32_e32 v116, v116
	v_lshlrev_b32_e32 v206, 16, v206
	v_mul_f32_e32 v206, v116, v206
	v_sub_f32_e32 v116, v136, v47
	v_mul_f32_e32 v116, 0x3fb8aa3b, v116
	v_exp_f32_e32 v116, v116
	v_lshlrev_b32_e32 v207, 16, v207
	v_mul_f32_e32 v207, v116, v207
	v_sub_f32_e32 v116, v136, v48
	v_mul_f32_e32 v116, 0x3fb8aa3b, v116
	v_exp_f32_e32 v116, v116
	v_lshlrev_b32_e32 v208, 16, v208
	v_mul_f32_e32 v208, v116, v208
	v_sub_f32_e32 v116, v136, v49
	v_mul_f32_e32 v116, 0x3fb8aa3b, v116
	v_exp_f32_e32 v116, v116
	v_lshlrev_b32_e32 v209, 16, v209
	v_mul_f32_e32 v209, v116, v209
	v_sub_f32_e32 v116, v136, v50
	v_mul_f32_e32 v116, 0x3fb8aa3b, v116
	v_exp_f32_e32 v116, v116
	v_lshlrev_b32_e32 v210, 16, v210
	v_mul_f32_e32 v210, v116, v210
	v_sub_f32_e32 v116, v136, v51
	v_mul_f32_e32 v116, 0x3fb8aa3b, v116
	v_exp_f32_e32 v116, v116
	v_lshlrev_b32_e32 v211, 16, v211
	v_mul_f32_e32 v211, v116, v211
	v_sub_f32_e32 v116, v136, v52
	v_mul_f32_e32 v116, 0x3fb8aa3b, v116
; DEVINL u16 f2bf(float a) { return (u16)(pk2(a, 0.f) & 0xffffu); }
; DEVINL float bf2f(u16 h) { return __uint_as_float(((unsigned)h) << 16); }
; DEVINL int fragpos(int idx) { const int w = idx & 31; return (idx & ~31) + (((w & 15) >> 2) << 3) + (w & 3) + ((w >> 4) << 2); }
; DEVINL void gla_prep_unit(const Params& p, int unit) {
;     ...
;     const float bedge = run;
;     const long hb = ((long)(dir * 2 + b) * 4 + h);
;     const int pk = fragpos(kk);
;     u16* qt = (u16*)(ws + O_QT) + (hb * 4096 + c * 64) * 128 + pk;
;     u16* kt = (u16*)(ws + O_KT) + (hb * 4096 + c * 64) * 128 + pk;
;     ((float*)(ws + O_DEC))[(hb * 64 + c) * 128 + kk] = __expf(bedge);
;     u16* KDr = KD + (dir * 128 + kk) * 72;
;     const unsigned short* qsrc = cols + tok0 * NCP + C_Q + h * 128 + kk;
;     const unsigned short* ksrc = cols + tok0 * NCP + C_K + h * 128 + kk;
; #pragma unroll 1
;     for (int i0 = 0; i0 < 64; i0 += 8) {
;       u16 qv[8], kv[8];
; #pragma unroll
;       for (int j = 0; j < 8; ++j) { qv[j] = qsrc[(long)(i0 + j) * NCP]; kv[j] = ksrc[(long)(i0 + j) * NCP]; }
; #pragma unroll
;       for (int j = 0; j < 8; ++j) {
;         const int i = i0 + j;
;         float bb = Gc[i * 128];
;         float q = bf2f(qv[j]);
;         float k = bf2f(kv[j]);
;         qt[i * 128] = f2bf(q * 0.08838834764831845f * __expf(bb));
;         kt[i * 128] = f2bf(k * __expf(-bb));
;         KDr[fragpos(i)] = f2bf(k * __expf(bedge - bb));
;       }
;     }
	v_exp_f32_e32 v116, v116
	v_lshlrev_b32_e32 v212, 16, v212
	v_mul_f32_e32 v212, v116, v212
	v_sub_f32_e32 v116, v136, v53
	v_mul_f32_e32 v116, 0x3fb8aa3b, v116
	v_exp_f32_e32 v116, v116
	v_lshlrev_b32_e32 v213, 16, v213
	v_mul_f32_e32 v213, v116, v213
	v_sub_f32_e32 v116, v136, v54
	v_mul_f32_e32 v116, 0x3fb8aa3b, v116
	v_exp_f32_e32 v116, v116
	v_lshlrev_b32_e32 v214, 16, v214
	v_mul_f32_e32 v214, v116, v214
	v_sub_f32_e32 v116, v136, v55
	v_mul_f32_e32 v116, 0x3fb8aa3b, v116
	v_exp_f32_e32 v116, v116
	v_lshlrev_b32_e32 v215, 16, v215
	v_mul_f32_e32 v215, v116, v215
	v_sub_f32_e32 v116, v136, v56
	v_mul_f32_e32 v116, 0x3fb8aa3b, v116
	v_exp_f32_e32 v116, v116
	v_lshlrev_b32_e32 v216, 16, v216
	v_mul_f32_e32 v216, v116, v216
	v_sub_f32_e32 v116, v136, v57
	v_mul_f32_e32 v116, 0x3fb8aa3b, v116
	v_exp_f32_e32 v116, v116
	v_lshlrev_b32_e32 v217, 16, v217
	v_mul_f32_e32 v217, v116, v217
	v_sub_f32_e32 v116, v136, v58
	v_mul_f32_e32 v116, 0x3fb8aa3b, v116
	v_exp_f32_e32 v116, v116
	v_lshlrev_b32_e32 v218, 16, v218
	v_mul_f32_e32 v218, v116, v218
	v_sub_f32_e32 v116, v136, v59
	v_mul_f32_e32 v116, 0x3fb8aa3b, v116
	v_exp_f32_e32 v116, v116
	v_lshlrev_b32_e32 v219, 16, v219
	v_mul_f32_e32 v219, v116, v219
	v_sub_f32_e32 v116, v136, v60
	v_mul_f32_e32 v116, 0x3fb8aa3b, v116
	v_exp_f32_e32 v116, v116
	v_lshlrev_b32_e32 v220, 16, v220
	v_mul_f32_e32 v220, v116, v220
	v_sub_f32_e32 v116, v136, v61
	v_mul_f32_e32 v116, 0x3fb8aa3b, v116
	v_exp_f32_e32 v116, v116
	v_lshlrev_b32_e32 v221, 16, v221
	v_mul_f32_e32 v221, v116, v221
	v_sub_f32_e32 v116, v136, v62
	v_mul_f32_e32 v116, 0x3fb8aa3b, v116
	v_exp_f32_e32 v116, v116
	v_lshlrev_b32_e32 v222, 16, v222
	v_mul_f32_e32 v222, v116, v222
	v_sub_f32_e32 v116, v136, v63
	v_mul_f32_e32 v116, 0x3fb8aa3b, v116
	v_exp_f32_e32 v116, v116
	v_lshlrev_b32_e32 v223, 16, v223
	v_mul_f32_e32 v223, v116, v223
	v_cvt_pk_bf16_f32 v144, v192, v193
	v_cvt_pk_bf16_f32 v145, v194, v195
	v_cvt_pk_bf16_f32 v146, v208, v209
	v_cvt_pk_bf16_f32 v147, v210, v211
	v_cvt_pk_bf16_f32 v148, v196, v197
	v_cvt_pk_bf16_f32 v149, v198, v199
	v_cvt_pk_bf16_f32 v150, v212, v213
	v_cvt_pk_bf16_f32 v151, v214, v215
	v_cvt_pk_bf16_f32 v152, v200, v201
	v_cvt_pk_bf16_f32 v153, v202, v203
	v_cvt_pk_bf16_f32 v154, v216, v217
	v_cvt_pk_bf16_f32 v155, v218, v219
	v_cvt_pk_bf16_f32 v156, v204, v205
	v_cvt_pk_bf16_f32 v157, v206, v207
	v_cvt_pk_bf16_f32 v158, v220, v221
	v_cvt_pk_bf16_f32 v159, v222, v223
	s_lshl_b32 s48, s71, 1
	s_add_u32 s48, s48, s43
	s_lshl_b32 s48, s48, 2
	s_add_u32 s48, s48, s41
	s_lshl_b32 s56, s48, 6
	s_add_u32 s56, s56, s42
	s_lshl_b32 s57, s56, 14
	s_add_u32 s58, s92, s57
	s_addc_u32 s59, s93, 0
	s_add_u32 s58, s58, 0x19400000
	s_addc_u32 s59, s59, 0
	global_store_dwordx4 v18, v[144:147], s[58:59] offset:0
	global_store_dwordx4 v18, v[148:151], s[58:59] offset:16
	global_store_dwordx4 v18, v[152:155], s[58:59] offset:32
	global_store_dwordx4 v18, v[156:159], s[58:59] offset:48
	s_cmp_eq_u32 s6, 0
	s_cbranch_scc0 .Lgl_nodec
	v_mul_f32_e32 v116, 0x3fb8aa3b, v136
	v_exp_f32_e32 v116, v116
	s_lshl_b32 s57, s56, 9
	s_add_u32 s58, s92, s57
	s_addc_u32 s59, s93, 0
	s_add_u32 s58, s58, 0x1b400000
	s_addc_u32 s59, s59, 0
	global_store_dword v7, v116, s[58:59]
.Lgl_nodec:
	s_waitcnt lgkmcnt(0)
	s_barrier
	s_mov_b32 s56, 0x3db504f3
	ds_read_b128 v[116:119], v22 offset:0
	ds_read_b128 v[120:123], v22 offset:64
	ds_read_b64 v[124:125], v23 offset:0
	ds_read_b64 v[126:127], v23 offset:32
	s_waitcnt lgkmcnt(0)
	v_lshlrev_b32_e32 v128, 16, v124
	v_and_b32_e32 v129, 0xffff0000, v124
	v_lshlrev_b32_e32 v130, 16, v125
	v_and_b32_e32 v131, 0xffff0000, v125
	v_lshlrev_b32_e32 v132, 16, v126
	v_and_b32_e32 v133, 0xffff0000, v126
	v_lshlrev_b32_e32 v134, 16, v127
	v_and_b32_e32 v135, 0xffff0000, v127
	v_mul_f32_e32 v116, 0x3fb8aa3b, v116
	v_exp_f32_e32 v116, v116
	v_mul_f32_e32 v128, s56, v128
	v_mul_f32_e32 v128, v128, v116
	v_mul_f32_e32 v117, 0x3fb8aa3b, v117
	v_exp_f32_e32 v117, v117
	v_mul_f32_e32 v129, s56, v129
	v_mul_f32_e32 v129, v129, v117
	v_mul_f32_e32 v118, 0x3fb8aa3b, v118
	v_exp_f32_e32 v118, v118
	v_mul_f32_e32 v130, s56, v130
	v_mul_f32_e32 v130, v130, v118
	v_mul_f32_e32 v119, 0x3fb8aa3b, v119
	v_exp_f32_e32 v119, v119
	v_mul_f32_e32 v131, s56, v131
	v_mul_f32_e32 v131, v131, v119
	v_mul_f32_e32 v120, 0x3fb8aa3b, v120
	v_exp_f32_e32 v120, v120
	v_mul_f32_e32 v132, s56, v132
	v_mul_f32_e32 v132, v132, v120
	v_mul_f32_e32 v121, 0x3fb8aa3b, v121
	v_exp_f32_e32 v121, v121
	v_mul_f32_e32 v133, s56, v133
	v_mul_f32_e32 v133, v133, v121
	v_mul_f32_e32 v122, 0x3fb8aa3b, v122
	v_exp_f32_e32 v122, v122
	v_mul_f32_e32 v134, s56, v134
	v_mul_f32_e32 v134, v134, v122
	v_mul_f32_e32 v123, 0x3fb8aa3b, v123
	v_exp_f32_e32 v123, v123
	v_mul_f32_e32 v135, s56, v135
	v_mul_f32_e32 v135, v135, v123
	v_cvt_pk_bf16_f32 v140, v128, v129
	v_cvt_pk_bf16_f32 v141, v130, v131
	v_cvt_pk_bf16_f32 v142, v132, v133
	v_cvt_pk_bf16_f32 v143, v134, v135
	s_lshl_b32 s48, s43, 2
	s_add_u32 s48, s48, 0
	s_add_u32 s48, s48, s41
	s_lshl_b32 s48, s48, 20
	s_lshl_b32 s57, s42, 14
	s_add_u32 s48, s48, s57
	s_add_u32 s48, s48, 0
	s_add_u32 s58, s92, s48
	s_addc_u32 s59, s93, 0
	s_add_u32 s58, s58, 0x17400000
	s_addc_u32 s59, s59, 0
	global_store_dwordx4 v2, v[140:143], s[58:59]
	ds_read_b128 v[116:119], v22 offset:16384
	ds_read_b128 v[120:123], v22 offset:16448
	ds_read_b64 v[124:125], v23 offset:8192
	ds_read_b64 v[126:127], v23 offset:8224
	s_waitcnt lgkmcnt(0)
; DEVINL u16 f2bf(float a) { return (u16)(pk2(a, 0.f) & 0xffffu); }
; DEVINL float bf2f(u16 h) { return __uint_as_float(((unsigned)h) << 16); }
; DEVINL void gla_prep_unit(const Params& p, int unit) {
;     ...
;         float bb = Gc[i * 128];
;         float q = bf2f(qv[j]);
;         float k = bf2f(kv[j]);
;         qt[i * 128] = f2bf(q * 0.08838834764831845f * __expf(bb));
;         kt[i * 128] = f2bf(k * __expf(-bb));
	v_lshlrev_b32_e32 v128, 16, v124
	v_and_b32_e32 v129, 0xffff0000, v124
	v_lshlrev_b32_e32 v130, 16, v125
	v_and_b32_e32 v131, 0xffff0000, v125
	v_lshlrev_b32_e32 v132, 16, v126
	v_and_b32_e32 v133, 0xffff0000, v126
	v_lshlrev_b32_e32 v134, 16, v127
	v_and_b32_e32 v135, 0xffff0000, v127
	v_mul_f32_e32 v116, 0x3fb8aa3b, v116
	v_exp_f32_e32 v116, v116
	v_mul_f32_e32 v128, s56, v128
	v_mul_f32_e32 v128, v128, v116
	v_mul_f32_e32 v117, 0x3fb8aa3b, v117
	v_exp_f32_e32 v117, v117
	v_mul_f32_e32 v129, s56, v129
	v_mul_f32_e32 v129, v129, v117
	v_mul_f32_e32 v118, 0x3fb8aa3b, v118
	v_exp_f32_e32 v118, v118
	v_mul_f32_e32 v130, s56, v130
	v_mul_f32_e32 v130, v130, v118
	v_mul_f32_e32 v119, 0x3fb8aa3b, v119
	v_exp_f32_e32 v119, v119
	v_mul_f32_e32 v131, s56, v131
	v_mul_f32_e32 v131, v131, v119
	v_mul_f32_e32 v120, 0x3fb8aa3b, v120
	v_exp_f32_e32 v120, v120
	v_mul_f32_e32 v132, s56, v132
	v_mul_f32_e32 v132, v132, v120
	v_mul_f32_e32 v121, 0x3fb8aa3b, v121
	v_exp_f32_e32 v121, v121
	v_mul_f32_e32 v133, s56, v133
	v_mul_f32_e32 v133, v133, v121
	v_mul_f32_e32 v122, 0x3fb8aa3b, v122
	v_exp_f32_e32 v122, v122
	v_mul_f32_e32 v134, s56, v134
	v_mul_f32_e32 v134, v134, v122
	v_mul_f32_e32 v123, 0x3fb8aa3b, v123
	v_exp_f32_e32 v123, v123
	v_mul_f32_e32 v135, s56, v135
	v_mul_f32_e32 v135, v135, v123
	v_cvt_pk_bf16_f32 v140, v128, v129
	v_cvt_pk_bf16_f32 v141, v130, v131
	v_cvt_pk_bf16_f32 v142, v132, v133
	v_cvt_pk_bf16_f32 v143, v134, v135
	s_lshl_b32 s48, s43, 2
	s_add_u32 s48, s48, 0
	s_add_u32 s48, s48, s41
	s_lshl_b32 s48, s48, 20
	s_lshl_b32 s57, s42, 14
	s_add_u32 s48, s48, s57
	s_add_u32 s48, s48, 8192
	s_add_u32 s58, s92, s48
	s_addc_u32 s59, s93, 0
	s_add_u32 s58, s58, 0x17400000
	s_addc_u32 s59, s59, 0
	global_store_dwordx4 v2, v[140:143], s[58:59]
	ds_read_b128 v[116:119], v22 offset:0
	ds_read_b128 v[120:123], v22 offset:64
	ds_read_b64 v[124:125], v23 offset:16384
	ds_read_b64 v[126:127], v23 offset:16416
	s_waitcnt lgkmcnt(0)
	v_lshlrev_b32_e32 v128, 16, v124
	v_and_b32_e32 v129, 0xffff0000, v124
	v_lshlrev_b32_e32 v130, 16, v125
	v_and_b32_e32 v131, 0xffff0000, v125
	v_lshlrev_b32_e32 v132, 16, v126
	v_and_b32_e32 v133, 0xffff0000, v126
	v_lshlrev_b32_e32 v134, 16, v127
	v_and_b32_e32 v135, 0xffff0000, v127
	v_mul_f32_e32 v116, 0xbfb8aa3b, v116
	v_exp_f32_e32 v116, v116
	s_nop 0
	v_mul_f32_e32 v128, v116, v128
	v_mul_f32_e32 v117, 0xbfb8aa3b, v117
	v_exp_f32_e32 v117, v117
	s_nop 0
	v_mul_f32_e32 v129, v117, v129
	v_mul_f32_e32 v118, 0xbfb8aa3b, v118
	v_exp_f32_e32 v118, v118
	s_nop 0
	v_mul_f32_e32 v130, v118, v130
	v_mul_f32_e32 v119, 0xbfb8aa3b, v119
	v_exp_f32_e32 v119, v119
	s_nop 0
	v_mul_f32_e32 v131, v119, v131
	v_mul_f32_e32 v120, 0xbfb8aa3b, v120
	v_exp_f32_e32 v120, v120
	s_nop 0
	v_mul_f32_e32 v132, v120, v132
	v_mul_f32_e32 v121, 0xbfb8aa3b, v121
	v_exp_f32_e32 v121, v121
	s_nop 0
	v_mul_f32_e32 v133, v121, v133
	v_mul_f32_e32 v122, 0xbfb8aa3b, v122
	v_exp_f32_e32 v122, v122
	s_nop 0
	v_mul_f32_e32 v134, v122, v134
	v_mul_f32_e32 v123, 0xbfb8aa3b, v123
	v_exp_f32_e32 v123, v123
	s_nop 0
	v_mul_f32_e32 v135, v123, v135
	v_cvt_pk_bf16_f32 v140, v128, v129
	v_cvt_pk_bf16_f32 v141, v130, v131
	v_cvt_pk_bf16_f32 v142, v132, v133
	v_cvt_pk_bf16_f32 v143, v134, v135
	s_lshl_b32 s48, s43, 2
	s_add_u32 s48, s48, 0
	s_add_u32 s48, s48, s41
	s_lshl_b32 s48, s48, 20
	s_lshl_b32 s57, s42, 14
	s_add_u32 s48, s48, s57
	s_add_u32 s48, s48, 0
	s_add_u32 s58, s92, s48
	s_addc_u32 s59, s93, 0
	s_add_u32 s58, s58, 0x18400000
	s_addc_u32 s59, s59, 0
	global_store_dwordx4 v2, v[140:143], s[58:59]
	ds_read_b128 v[116:119], v22 offset:16384
	ds_read_b128 v[120:123], v22 offset:16448
	ds_read_b64 v[124:125], v23 offset:24576
	ds_read_b64 v[126:127], v23 offset:24608
	s_waitcnt lgkmcnt(0)
	v_lshlrev_b32_e32 v128, 16, v124
	v_and_b32_e32 v129, 0xffff0000, v124
	v_lshlrev_b32_e32 v130, 16, v125
	v_and_b32_e32 v131, 0xffff0000, v125
	v_lshlrev_b32_e32 v132, 16, v126
	v_and_b32_e32 v133, 0xffff0000, v126
	v_lshlrev_b32_e32 v134, 16, v127
	v_and_b32_e32 v135, 0xffff0000, v127
	v_mul_f32_e32 v116, 0xbfb8aa3b, v116
	v_exp_f32_e32 v116, v116
	s_nop 0
	v_mul_f32_e32 v128, v116, v128
	v_mul_f32_e32 v117, 0xbfb8aa3b, v117
	v_exp_f32_e32 v117, v117
	s_nop 0
	v_mul_f32_e32 v129, v117, v129
	v_mul_f32_e32 v118, 0xbfb8aa3b, v118
	v_exp_f32_e32 v118, v118
	s_nop 0
	v_mul_f32_e32 v130, v118, v130
	v_mul_f32_e32 v119, 0xbfb8aa3b, v119
	v_exp_f32_e32 v119, v119
	s_nop 0
	v_mul_f32_e32 v131, v119, v131
	v_mul_f32_e32 v120, 0xbfb8aa3b, v120
	v_exp_f32_e32 v120, v120
	s_nop 0
	v_mul_f32_e32 v132, v120, v132
	v_mul_f32_e32 v121, 0xbfb8aa3b, v121
	v_exp_f32_e32 v121, v121
	s_nop 0
	v_mul_f32_e32 v133, v121, v133
	v_mul_f32_e32 v122, 0xbfb8aa3b, v122
	v_exp_f32_e32 v122, v122
	s_nop 0
	v_mul_f32_e32 v134, v122, v134
	v_mul_f32_e32 v123, 0xbfb8aa3b, v123
	v_exp_f32_e32 v123, v123
	s_nop 0
	v_mul_f32_e32 v135, v123, v135
	v_cvt_pk_bf16_f32 v140, v128, v129
	v_cvt_pk_bf16_f32 v141, v130, v131
	v_cvt_pk_bf16_f32 v142, v132, v133
	v_cvt_pk_bf16_f32 v143, v134, v135
	s_lshl_b32 s48, s43, 2
	s_add_u32 s48, s48, 0
	s_add_u32 s48, s48, s41
	s_lshl_b32 s48, s48, 20
	s_lshl_b32 s57, s42, 14
	s_add_u32 s48, s48, s57
	s_add_u32 s48, s48, 8192
	s_add_u32 s58, s92, s48
	s_addc_u32 s59, s93, 0
	s_add_u32 s58, s58, 0x18400000
	s_addc_u32 s59, s59, 0
	global_store_dwordx4 v2, v[140:143], s[58:59]
	ds_read_b128 v[116:119], v22 offset:32768
	ds_read_b128 v[120:123], v22 offset:32832
	ds_read_b64 v[124:125], v23 offset:0
	ds_read_b64 v[126:127], v23 offset:32
	s_waitcnt lgkmcnt(0)
; DEVINL u16 f2bf(float a) { return (u16)(pk2(a, 0.f) & 0xffffu); }
; DEVINL float bf2f(u16 h) { return __uint_as_float(((unsigned)h) << 16); }
; DEVINL void gla_prep_unit(const Params& p, int unit) {
;     ...
;         float bb = Gc[i * 128];
;         float q = bf2f(qv[j]);
;         float k = bf2f(kv[j]);
;         qt[i * 128] = f2bf(q * 0.08838834764831845f * __expf(bb));
;         kt[i * 128] = f2bf(k * __expf(-bb));
	v_lshlrev_b32_e32 v128, 16, v124
	v_and_b32_e32 v129, 0xffff0000, v124
	v_lshlrev_b32_e32 v130, 16, v125
	v_and_b32_e32 v131, 0xffff0000, v125
	v_lshlrev_b32_e32 v132, 16, v126
	v_and_b32_e32 v133, 0xffff0000, v126
	v_lshlrev_b32_e32 v134, 16, v127
	v_and_b32_e32 v135, 0xffff0000, v127
	v_mul_f32_e32 v116, 0x3fb8aa3b, v116
	v_exp_f32_e32 v116, v116
	v_mul_f32_e32 v128, s56, v128
	v_mul_f32_e32 v128, v128, v116
	v_mul_f32_e32 v117, 0x3fb8aa3b, v117
	v_exp_f32_e32 v117, v117
	v_mul_f32_e32 v129, s56, v129
	v_mul_f32_e32 v129, v129, v117
	v_mul_f32_e32 v118, 0x3fb8aa3b, v118
	v_exp_f32_e32 v118, v118
	v_mul_f32_e32 v130, s56, v130
	v_mul_f32_e32 v130, v130, v118
	v_mul_f32_e32 v119, 0x3fb8aa3b, v119
	v_exp_f32_e32 v119, v119
	v_mul_f32_e32 v131, s56, v131
	v_mul_f32_e32 v131, v131, v119
	v_mul_f32_e32 v120, 0x3fb8aa3b, v120
	v_exp_f32_e32 v120, v120
	v_mul_f32_e32 v132, s56, v132
	v_mul_f32_e32 v132, v132, v120
	v_mul_f32_e32 v121, 0x3fb8aa3b, v121
	v_exp_f32_e32 v121, v121
	v_mul_f32_e32 v133, s56, v133
	v_mul_f32_e32 v133, v133, v121
	v_mul_f32_e32 v122, 0x3fb8aa3b, v122
	v_exp_f32_e32 v122, v122
	v_mul_f32_e32 v134, s56, v134
	v_mul_f32_e32 v134, v134, v122
	v_mul_f32_e32 v123, 0x3fb8aa3b, v123
	v_exp_f32_e32 v123, v123
	v_mul_f32_e32 v135, s56, v135
	v_mul_f32_e32 v135, v135, v123
	v_cvt_pk_bf16_f32 v140, v128, v129
	v_cvt_pk_bf16_f32 v141, v130, v131
	v_cvt_pk_bf16_f32 v142, v132, v133
	v_cvt_pk_bf16_f32 v143, v134, v135
	s_lshl_b32 s48, s43, 2
	s_add_u32 s48, s48, 8
	s_add_u32 s48, s48, s41
	s_lshl_b32 s48, s48, 20
	s_lshl_b32 s57, s42, 14
	s_add_u32 s48, s48, s57
	s_add_u32 s48, s48, 0
	s_add_u32 s58, s92, s48
	s_addc_u32 s59, s93, 0
	s_add_u32 s58, s58, 0x17400000
	s_addc_u32 s59, s59, 0
	global_store_dwordx4 v2, v[140:143], s[58:59]
	ds_read_b128 v[116:119], v22 offset:49152
	ds_read_b128 v[120:123], v22 offset:49216
	ds_read_b64 v[124:125], v23 offset:8192
	ds_read_b64 v[126:127], v23 offset:8224
	s_waitcnt lgkmcnt(0)
	v_lshlrev_b32_e32 v128, 16, v124
	v_and_b32_e32 v129, 0xffff0000, v124
	v_lshlrev_b32_e32 v130, 16, v125
	v_and_b32_e32 v131, 0xffff0000, v125
	v_lshlrev_b32_e32 v132, 16, v126
	v_and_b32_e32 v133, 0xffff0000, v126
	v_lshlrev_b32_e32 v134, 16, v127
	v_and_b32_e32 v135, 0xffff0000, v127
	v_mul_f32_e32 v116, 0x3fb8aa3b, v116
	v_exp_f32_e32 v116, v116
	v_mul_f32_e32 v128, s56, v128
	v_mul_f32_e32 v128, v128, v116
	v_mul_f32_e32 v117, 0x3fb8aa3b, v117
	v_exp_f32_e32 v117, v117
	v_mul_f32_e32 v129, s56, v129
	v_mul_f32_e32 v129, v129, v117
	v_mul_f32_e32 v118, 0x3fb8aa3b, v118
	v_exp_f32_e32 v118, v118
	v_mul_f32_e32 v130, s56, v130
	v_mul_f32_e32 v130, v130, v118
	v_mul_f32_e32 v119, 0x3fb8aa3b, v119
	v_exp_f32_e32 v119, v119
	v_mul_f32_e32 v131, s56, v131
	v_mul_f32_e32 v131, v131, v119
	v_mul_f32_e32 v120, 0x3fb8aa3b, v120
	v_exp_f32_e32 v120, v120
	v_mul_f32_e32 v132, s56, v132
	v_mul_f32_e32 v132, v132, v120
	v_mul_f32_e32 v121, 0x3fb8aa3b, v121
	v_exp_f32_e32 v121, v121
	v_mul_f32_e32 v133, s56, v133
	v_mul_f32_e32 v133, v133, v121
	v_mul_f32_e32 v122, 0x3fb8aa3b, v122
	v_exp_f32_e32 v122, v122
	v_mul_f32_e32 v134, s56, v134
	v_mul_f32_e32 v134, v134, v122
	v_mul_f32_e32 v123, 0x3fb8aa3b, v123
	v_exp_f32_e32 v123, v123
	v_mul_f32_e32 v135, s56, v135
	v_mul_f32_e32 v135, v135, v123
	v_cvt_pk_bf16_f32 v140, v128, v129
	v_cvt_pk_bf16_f32 v141, v130, v131
	v_cvt_pk_bf16_f32 v142, v132, v133
	v_cvt_pk_bf16_f32 v143, v134, v135
	s_lshl_b32 s48, s43, 2
	s_add_u32 s48, s48, 8
	s_add_u32 s48, s48, s41
	s_lshl_b32 s48, s48, 20
	s_lshl_b32 s57, s42, 14
	s_add_u32 s48, s48, s57
	s_add_u32 s48, s48, 8192
	s_add_u32 s58, s92, s48
	s_addc_u32 s59, s93, 0
	s_add_u32 s58, s58, 0x17400000
	s_addc_u32 s59, s59, 0
	global_store_dwordx4 v2, v[140:143], s[58:59]
	ds_read_b128 v[116:119], v22 offset:32768
	ds_read_b128 v[120:123], v22 offset:32832
	ds_read_b64 v[124:125], v23 offset:16384
	ds_read_b64 v[126:127], v23 offset:16416
	s_waitcnt lgkmcnt(0)
; DEVINL u16 f2bf(float a) { return (u16)(pk2(a, 0.f) & 0xffffu); }
; DEVINL float bf2f(u16 h) { return __uint_as_float(((unsigned)h) << 16); }
; DEVINL void gla_prep_unit(const Params& p, int unit) {
;     ...
;         float bb = Gc[i * 128];
;         float q = bf2f(qv[j]);
;         float k = bf2f(kv[j]);
;         qt[i * 128] = f2bf(q * 0.08838834764831845f * __expf(bb));
;         kt[i * 128] = f2bf(k * __expf(-bb));
	v_lshlrev_b32_e32 v128, 16, v124
	v_and_b32_e32 v129, 0xffff0000, v124
	v_lshlrev_b32_e32 v130, 16, v125
	v_and_b32_e32 v131, 0xffff0000, v125
	v_lshlrev_b32_e32 v132, 16, v126
	v_and_b32_e32 v133, 0xffff0000, v126
	v_lshlrev_b32_e32 v134, 16, v127
	v_and_b32_e32 v135, 0xffff0000, v127
	v_mul_f32_e32 v116, 0xbfb8aa3b, v116
	v_exp_f32_e32 v116, v116
	s_nop 0
	v_mul_f32_e32 v128, v116, v128
	v_mul_f32_e32 v117, 0xbfb8aa3b, v117
	v_exp_f32_e32 v117, v117
	s_nop 0
	v_mul_f32_e32 v129, v117, v129
	v_mul_f32_e32 v118, 0xbfb8aa3b, v118
	v_exp_f32_e32 v118, v118
	s_nop 0
	v_mul_f32_e32 v130, v118, v130
	v_mul_f32_e32 v119, 0xbfb8aa3b, v119
	v_exp_f32_e32 v119, v119
	s_nop 0
	v_mul_f32_e32 v131, v119, v131
	v_mul_f32_e32 v120, 0xbfb8aa3b, v120
	v_exp_f32_e32 v120, v120
	s_nop 0
	v_mul_f32_e32 v132, v120, v132
	v_mul_f32_e32 v121, 0xbfb8aa3b, v121
	v_exp_f32_e32 v121, v121
	s_nop 0
	v_mul_f32_e32 v133, v121, v133
	v_mul_f32_e32 v122, 0xbfb8aa3b, v122
	v_exp_f32_e32 v122, v122
	s_nop 0
	v_mul_f32_e32 v134, v122, v134
	v_mul_f32_e32 v123, 0xbfb8aa3b, v123
	v_exp_f32_e32 v123, v123
	s_nop 0
	v_mul_f32_e32 v135, v123, v135
	v_cvt_pk_bf16_f32 v140, v128, v129
	v_cvt_pk_bf16_f32 v141, v130, v131
	v_cvt_pk_bf16_f32 v142, v132, v133
	v_cvt_pk_bf16_f32 v143, v134, v135
	s_lshl_b32 s48, s43, 2
	s_add_u32 s48, s48, 8
	s_add_u32 s48, s48, s41
	s_lshl_b32 s48, s48, 20
	s_lshl_b32 s57, s42, 14
	s_add_u32 s48, s48, s57
	s_add_u32 s48, s48, 0
	s_add_u32 s58, s92, s48
	s_addc_u32 s59, s93, 0
	s_add_u32 s58, s58, 0x18400000
	s_addc_u32 s59, s59, 0
	global_store_dwordx4 v2, v[140:143], s[58:59]
	ds_read_b128 v[116:119], v22 offset:49152
	ds_read_b128 v[120:123], v22 offset:49216
	ds_read_b64 v[124:125], v23 offset:24576
	ds_read_b64 v[126:127], v23 offset:24608
	s_waitcnt lgkmcnt(0)
	v_lshlrev_b32_e32 v128, 16, v124
	v_and_b32_e32 v129, 0xffff0000, v124
	v_lshlrev_b32_e32 v130, 16, v125
	v_and_b32_e32 v131, 0xffff0000, v125
	v_lshlrev_b32_e32 v132, 16, v126
	v_and_b32_e32 v133, 0xffff0000, v126
	v_lshlrev_b32_e32 v134, 16, v127
	v_and_b32_e32 v135, 0xffff0000, v127
	v_mul_f32_e32 v116, 0xbfb8aa3b, v116
	v_exp_f32_e32 v116, v116
	s_nop 0
	v_mul_f32_e32 v128, v116, v128
	v_mul_f32_e32 v117, 0xbfb8aa3b, v117
	v_exp_f32_e32 v117, v117
	s_nop 0
	v_mul_f32_e32 v129, v117, v129
	v_mul_f32_e32 v118, 0xbfb8aa3b, v118
	v_exp_f32_e32 v118, v118
	s_nop 0
	v_mul_f32_e32 v130, v118, v130
	v_mul_f32_e32 v119, 0xbfb8aa3b, v119
	v_exp_f32_e32 v119, v119
	s_nop 0
	v_mul_f32_e32 v131, v119, v131
	v_mul_f32_e32 v120, 0xbfb8aa3b, v120
	v_exp_f32_e32 v120, v120
	s_nop 0
	v_mul_f32_e32 v132, v120, v132
	v_mul_f32_e32 v121, 0xbfb8aa3b, v121
	v_exp_f32_e32 v121, v121
	s_nop 0
	v_mul_f32_e32 v133, v121, v133
	v_mul_f32_e32 v122, 0xbfb8aa3b, v122
	v_exp_f32_e32 v122, v122
	s_nop 0
	v_mul_f32_e32 v134, v122, v134
	v_mul_f32_e32 v123, 0xbfb8aa3b, v123
	v_exp_f32_e32 v123, v123
	s_nop 0
	v_mul_f32_e32 v135, v123, v135
	v_cvt_pk_bf16_f32 v140, v128, v129
	v_cvt_pk_bf16_f32 v141, v130, v131
	v_cvt_pk_bf16_f32 v142, v132, v133
	v_cvt_pk_bf16_f32 v143, v134, v135
	s_lshl_b32 s48, s43, 2
	s_add_u32 s48, s48, 8
	s_add_u32 s48, s48, s41
	s_lshl_b32 s48, s48, 20
	s_lshl_b32 s57, s42, 14
	s_add_u32 s48, s48, s57
	s_add_u32 s48, s48, 8192
	s_add_u32 s58, s92, s48
	s_addc_u32 s59, s93, 0
	s_add_u32 s58, s58, 0x18400000
	s_addc_u32 s59, s59, 0
	global_store_dwordx4 v2, v[140:143], s[58:59]
	s_branch .Lgl_unit

; template <int DIR>
; DEVINL void rwkv_scan_dir(const Params& p, int task, int lane, int wave) {
;   const int b = (task >> 8) & 1, head = (task >> 4) & 15, rg = task & 15;
;   const int seg = lane & 15, rl = lane >> 4, row = rg * 4 + rl;
;   constexpr int DIST = 24;
;   constexpr int WOFS = DIR ? 8 : 0;
;   const char* recbase = p.ws + O_REC + ((long)(b * 16 + head) * 4096) * 1024 + lane * 16;
;   const unsigned ring_lds = (unsigned)(unsigned long)(__attribute__((address_space(3))) char*)(dynsmem + wave * 32768);
;   const unsigned ring_u = __builtin_amdgcn_readfirstlane(ring_lds);
;   const unsigned a_seg = ring_lds + seg * 64;
;   const unsigned a_v = ring_lds + (row >> 2) * 64 + 48 + (row & 3) * 2;
;   u16* yo = (u16*)(p.ws + (DIR ? O_YB : O_YSUM)) + ((long)b * 4096) * 1024 + head * 64 + row;
.LBB0_481:
	s_andn2_saveexec_b64 s[0:1], s[20:21]
	s_cbranch_execz .LBB0_498
	s_setprio 3
	v_and_b32_e32 v3, 15, v0
	v_lshrrev_b32_e32 v4, 4, v0
	v_lshlrev_b32_e32 v5, 4, v0
	v_readfirstlane_b32 s6, v2
	s_nop 3
	s_lshl_b32 s7, s38, 2
	s_add_u32 s7, s7, s6
	s_lshl_b32 s8, s94, 2
	s_mov_b32 s48, 0xaaaaaaaa
	s_mov_b32 s49, 0xaaaaaaaa
	s_mov_b32 s50, 0xcccccccc
	s_mov_b32 s51, 0xcccccccc
	v_mov_b32_e32 v9, 0x20010
	s_lshl_b32 s3, s6, 2
	s_add_u32 s3, s3, 0x20010
	v_mov_b32_e32 v23, s3
	v_add_u32_e32 v68, 16, v23
	s_mov_b32 s15, 0

; DEVINL void phase3(const Params& p) {
;     ...
;   if (wave < 4) {
;     for (int task = vb * 4 + wave; task < 1024; task += nb * 4) rwkv_scan_task(p, task, lane, wave);
.Lrw_done:
	s_setprio 0

; #define LAS __attribute__((address_space(3)))
; __global__ void __launch_bounds__(512, 2) k_mega(Params p) {
;   cg::grid_group grid = cg::this_grid();
;   __shared__ uint4 xb_words;
;   unsigned* bar = (unsigned*)(p.ws + O_BAR);
;   if (threadIdx.x == 0) xb_words = make_uint4(0u, 0u, 0u, 0u);
;   __syncthreads();
;   XcdBarrier xb = xcd_barrier_post(bar, (volatile LAS unsigned*)&xb_words);
;   if (p.out == nullptr) grid.sync();
;   run_phase<0>(p); xcd_barrier(xb);
;   run_phase<1>(p); xcd_barrier(xb);
;   run_phase<2>(p); xcd_barrier(xb);
;   run_phase<3>(p); xcd_barrier(xb);
;   run_phase<4>(p); xcd_barrier(xb);
;   run_phase<5>(p); xcd_barrier(xb);
;   run_phase<6>(p); xcd_barrier(xb);
;   run_phase<7>(p); xcd_barrier(xb);
;   run_phase<8>(p); xcd_barrier(xb);
;   run_phase<9>(p); xcd_barrier(xb);
;   run_phase<10>(p); xcd_barrier(xb);
;   run_phase<11>(p);
; }
	.amdhsa_kernel _Z6k_mega6Params
		.amdhsa_group_segment_fixed_size 8208
		.amdhsa_private_segment_fixed_size 0
		.amdhsa_kernarg_size 520
		.amdhsa_user_sgpr_count 2
		.amdhsa_user_sgpr_dispatch_ptr 0
		.amdhsa_user_sgpr_queue_ptr 0
		.amdhsa_user_sgpr_kernarg_segment_ptr 1
		.amdhsa_user_sgpr_dispatch_id 0
		.amdhsa_user_sgpr_kernarg_preload_length 0
		.amdhsa_user_sgpr_kernarg_preload_offset 0
		.amdhsa_user_sgpr_private_segment_size 0
		.amdhsa_uses_dynamic_stack 0
		.amdhsa_enable_private_segment 0
		.amdhsa_system_sgpr_workgroup_id_x 1
		.amdhsa_system_sgpr_workgroup_id_y 0
		.amdhsa_system_sgpr_workgroup_id_z 0
		.amdhsa_system_sgpr_workgroup_info 0
		.amdhsa_system_vgpr_workitem_id 2
		.amdhsa_next_free_vgpr 256
		.amdhsa_next_free_sgpr 99
		.amdhsa_accum_offset 256
		.amdhsa_reserve_vcc 1
		.amdhsa_float_round_mode_32 0
		.amdhsa_float_round_mode_16_64 0
		.amdhsa_float_denorm_mode_32 3
		.amdhsa_float_denorm_mode_16_64 3
		.amdhsa_dx10_clamp 1
		.amdhsa_ieee_mode 1
		.amdhsa_fp16_overflow 0
		.amdhsa_tg_split 0
		.amdhsa_exception_fp_ieee_invalid_op 0
		.amdhsa_exception_fp_denorm_src 0
		.amdhsa_exception_fp_ieee_div_zero 0
		.amdhsa_exception_fp_ieee_overflow 0
		.amdhsa_exception_fp_ieee_underflow 0
		.amdhsa_exception_fp_ieee_inexact 0
		.amdhsa_exception_int_div_zero 0
	.end_amdhsa_kernel

; #define LAS __attribute__((address_space(3)))
; __global__ void __launch_bounds__(512, 2) k_mega(Params p) {
;   cg::grid_group grid = cg::this_grid();
;   __shared__ uint4 xb_words;
;   unsigned* bar = (unsigned*)(p.ws + O_BAR);
;   if (threadIdx.x == 0) xb_words = make_uint4(0u, 0u, 0u, 0u);
;   __syncthreads();
;   XcdBarrier xb = xcd_barrier_post(bar, (volatile LAS unsigned*)&xb_words);
;   if (p.out == nullptr) grid.sync();
;   run_phase<0>(p); xcd_barrier(xb);
;   run_phase<1>(p); xcd_barrier(xb);
;   run_phase<2>(p); xcd_barrier(xb);
;   run_phase<3>(p); xcd_barrier(xb);
;   run_phase<4>(p); xcd_barrier(xb);
;   run_phase<5>(p); xcd_barrier(xb);
;   run_phase<6>(p); xcd_barrier(xb);
;   run_phase<7>(p); xcd_barrier(xb);
;   run_phase<8>(p); xcd_barrier(xb);
;   run_phase<9>(p); xcd_barrier(xb);
;   run_phase<10>(p); xcd_barrier(xb);
;   run_phase<11>(p);
; }
amdhsa.kernels:
  - .agpr_count:     0
    .args:
      - .offset:         0
        .size:           264
        .value_kind:     by_value
      - .offset:         264
        .size:           4
        .value_kind:     hidden_block_count_x
      - .offset:         268
        .size:           4
        .value_kind:     hidden_block_count_y
      - .offset:         272
        .size:           4
        .value_kind:     hidden_block_count_z
      - .offset:         276
        .size:           2
        .value_kind:     hidden_group_size_x
      - .offset:         278
        .size:           2
        .value_kind:     hidden_group_size_y
      - .offset:         280
        .size:           2
        .value_kind:     hidden_group_size_z
      - .offset:         282
        .size:           2
        .value_kind:     hidden_remainder_x
      - .offset:         284
        .size:           2
        .value_kind:     hidden_remainder_y
      - .offset:         286
        .size:           2
        .value_kind:     hidden_remainder_z
      - .offset:         304
        .size:           8
        .value_kind:     hidden_global_offset_x
      - .offset:         312
        .size:           8
        .value_kind:     hidden_global_offset_y
      - .offset:         320
        .size:           8
        .value_kind:     hidden_global_offset_z
      - .offset:         328
        .size:           2
        .value_kind:     hidden_grid_dims
      - .offset:         352
        .size:           8
        .value_kind:     hidden_multigrid_sync_arg
      - .offset:         384
        .size:           4
        .value_kind:     hidden_dynamic_lds_size
    .group_segment_fixed_size: 8208
    .kernarg_segment_align: 8
    .kernarg_segment_size: 520
    .language:       OpenCL C
    .language_version:
      - 2
      - 0
    .max_flat_workgroup_size: 512
    .name:           _Z6k_mega6Params
    .private_segment_fixed_size: 0
    .sgpr_count:     105
    .sgpr_spill_count: 20
    .symbol:         _Z6k_mega6Params.kd
    .uniform_work_group_size: 1
    .uses_dynamic_stack: false
    .vgpr_count:     256
    .vgpr_spill_count: 0
    .wavefront_size: 64
